# all 80 per-segment s_setprio toggles removed from the five GEMM K-loops (priority stays 0)
# speedup vs baseline: 1.0044x; 1.0044x over previous
.LBB0_207:
	ds_read_b128 v[156:159], v152
	ds_read_b128 v[160:163], v152 offset:1024
	ds_read_b128 v[164:167], v152 offset:2048
	ds_read_b128 v[168:171], v152 offset:3072
	ds_read_b128 v[172:175], v153
	ds_read_b128 v[176:179], v153 offset:1024
	ds_read_b128 v[180:183], v153 offset:2048
	ds_read_b128 v[184:187], v153 offset:3072
	s_add_u32 s36, s0, 0xfffe0080
	s_addc_u32 s37, s1, -1
	s_cmp_eq_u32 s62, 4
	s_cselect_b32 s39, s25, s37
	s_cselect_b32 s38, s27, s36
	s_cselect_b32 s37, s29, s61
	s_cselect_b32 s36, s28, s60
	v_lshl_add_u64 v[146:147], s[0:1], 0, v[138:139]
	s_add_i32 m0, s35, 0xc000
	ds_read_b128 v[188:191], v154
	ds_read_b128 v[192:195], v154 offset:1024
	ds_read_b128 v[196:199], v154 offset:2048
	ds_read_b128 v[200:203], v154 offset:3072
	ds_read_b128 v[204:207], v154 offset:4096
	ds_read_b128 v[208:211], v154 offset:5120
	ds_read_b128 v[212:215], v154 offset:6144
	ds_read_b128 v[216:219], v154 offset:7168
	global_load_lds_dwordx4 v[146:147], off
	v_lshl_add_u64 v[146:147], s[0:1], 0, v[140:141]
	s_add_i32 m0, s35, 0xe000
	s_nop 0
	global_load_lds_dwordx4 v[146:147], off
	s_waitcnt vmcnt(8)
	s_waitcnt lgkmcnt(0)
	s_barrier

	s_waitcnt lgkmcnt(0)
	v_mfma_f32_16x16x32_bf16 v[126:129], v[156:159], v[188:191], v[126:129]
	v_mfma_f32_16x16x32_bf16 v[122:125], v[164:167], v[188:191], v[122:125]
	v_mfma_f32_16x16x32_bf16 v[118:121], v[156:159], v[196:199], v[118:121]
	v_mfma_f32_16x16x32_bf16 v[110:113], v[164:167], v[196:199], v[110:113]
	v_mfma_f32_16x16x32_bf16 v[102:105], v[156:159], v[204:207], v[102:105]
	v_mfma_f32_16x16x32_bf16 v[94:97], v[164:167], v[204:207], v[94:97]
	v_mfma_f32_16x16x32_bf16 v[86:89], v[156:159], v[212:215], v[86:89]
	v_mfma_f32_16x16x32_bf16 v[78:81], v[164:167], v[212:215], v[78:81]
	v_mfma_f32_16x16x32_bf16 v[126:129], v[160:163], v[192:195], v[126:129]
	v_mfma_f32_16x16x32_bf16 v[122:125], v[168:171], v[192:195], v[122:125]
	v_mfma_f32_16x16x32_bf16 v[118:121], v[160:163], v[200:203], v[118:121]
	v_mfma_f32_16x16x32_bf16 v[110:113], v[168:171], v[200:203], v[110:113]
	v_mfma_f32_16x16x32_bf16 v[102:105], v[160:163], v[208:211], v[102:105]
	v_mfma_f32_16x16x32_bf16 v[94:97], v[168:171], v[208:211], v[94:97]
	v_mfma_f32_16x16x32_bf16 v[86:89], v[160:163], v[216:219], v[86:89]
	v_mfma_f32_16x16x32_bf16 v[78:81], v[168:171], v[216:219], v[78:81]


	v_mfma_f32_16x16x32_bf16 v[114:117], v[172:175], v[188:191], v[114:117]
	v_mfma_f32_16x16x32_bf16 v[106:109], v[180:183], v[188:191], v[106:109]
	v_mfma_f32_16x16x32_bf16 v[98:101], v[172:175], v[196:199], v[98:101]
	v_mfma_f32_16x16x32_bf16 v[90:93], v[180:183], v[196:199], v[90:93]
	v_mfma_f32_16x16x32_bf16 v[82:85], v[172:175], v[204:207], v[82:85]
	v_mfma_f32_16x16x32_bf16 v[74:77], v[180:183], v[204:207], v[74:77]
	v_mfma_f32_16x16x32_bf16 v[70:73], v[172:175], v[212:215], v[70:73]
	v_mfma_f32_16x16x32_bf16 v[66:69], v[180:183], v[212:215], v[66:69]
	v_mfma_f32_16x16x32_bf16 v[114:117], v[176:179], v[192:195], v[114:117]
	v_mfma_f32_16x16x32_bf16 v[106:109], v[184:187], v[192:195], v[106:109]
	v_mfma_f32_16x16x32_bf16 v[98:101], v[176:179], v[200:203], v[98:101]
	v_mfma_f32_16x16x32_bf16 v[90:93], v[184:187], v[200:203], v[90:93]
	v_mfma_f32_16x16x32_bf16 v[82:85], v[176:179], v[208:211], v[82:85]
	v_mfma_f32_16x16x32_bf16 v[74:77], v[184:187], v[208:211], v[74:77]
	v_mfma_f32_16x16x32_bf16 v[70:73], v[176:179], v[216:219], v[70:73]
	v_mfma_f32_16x16x32_bf16 v[66:69], v[184:187], v[216:219], v[66:69]

	s_barrier
	s_add_i32 s63, s53, s43
	v_lshl_add_u64 v[146:147], s[36:37], 0, v[132:133]
	s_mov_b32 m0, s63
	ds_read_b128 v[188:191], v154 offset:16384
	ds_read_b128 v[192:195], v154 offset:17408
	ds_read_b128 v[196:199], v154 offset:18432
	ds_read_b128 v[200:203], v154 offset:19456
	ds_read_b128 v[204:207], v154 offset:20480
	ds_read_b128 v[208:211], v154 offset:21504
	ds_read_b128 v[212:215], v154 offset:22528
	ds_read_b128 v[216:219], v154 offset:23552
	global_load_lds_dwordx4 v[146:147], off
	s_add_i32 m0, s63, 0x2000
	s_add_u32 s64, s36, 0x80000
	v_lshl_add_u64 v[220:221], s[36:37], 0, v[136:137]
	s_addc_u32 s65, s37, 0
	s_add_i32 s63, s54, s43
	global_load_lds_dwordx4 v[220:221], off
	v_lshl_add_u64 v[222:223], s[64:65], 0, v[132:133]
	s_mov_b32 m0, s63
	v_lshl_add_u64 v[224:225], s[38:39], 0, v[134:135]
	global_load_lds_dwordx4 v[222:223], off
	v_lshl_add_u64 v[222:223], s[64:65], 0, v[136:137]
	s_add_i32 m0, s63, 0x2000
	s_nop 0
	global_load_lds_dwordx4 v[222:223], off
	v_lshl_add_u64 v[222:223], s[38:39], 0, v[130:131]
	s_mov_b32 m0, s35
	s_nop 0
	global_load_lds_dwordx4 v[222:223], off
	s_mov_b32 m0, s46
	s_nop 0
	global_load_lds_dwordx4 v[224:225], off
	s_waitcnt vmcnt(8)
	s_waitcnt lgkmcnt(0)
	s_barrier

	s_waitcnt lgkmcnt(0)
	v_mfma_f32_16x16x32_bf16 v[62:65], v[156:159], v[188:191], v[62:65]
	v_mfma_f32_16x16x32_bf16 v[58:61], v[164:167], v[188:191], v[58:61]
	v_mfma_f32_16x16x32_bf16 v[54:57], v[156:159], v[196:199], v[54:57]
	v_mfma_f32_16x16x32_bf16 v[46:49], v[164:167], v[196:199], v[46:49]
	v_mfma_f32_16x16x32_bf16 v[38:41], v[156:159], v[204:207], v[38:41]
	v_mfma_f32_16x16x32_bf16 v[30:33], v[164:167], v[204:207], v[30:33]
	v_mfma_f32_16x16x32_bf16 v[22:25], v[156:159], v[212:215], v[22:25]
	v_mfma_f32_16x16x32_bf16 v[14:17], v[164:167], v[212:215], v[14:17]
	v_mfma_f32_16x16x32_bf16 v[62:65], v[160:163], v[192:195], v[62:65]
	v_mfma_f32_16x16x32_bf16 v[58:61], v[168:171], v[192:195], v[58:61]
	v_mfma_f32_16x16x32_bf16 v[54:57], v[160:163], v[200:203], v[54:57]
	v_mfma_f32_16x16x32_bf16 v[46:49], v[168:171], v[200:203], v[46:49]
	v_mfma_f32_16x16x32_bf16 v[38:41], v[160:163], v[208:211], v[38:41]
	v_mfma_f32_16x16x32_bf16 v[30:33], v[168:171], v[208:211], v[30:33]
	v_mfma_f32_16x16x32_bf16 v[22:25], v[160:163], v[216:219], v[22:25]
	v_mfma_f32_16x16x32_bf16 v[14:17], v[168:171], v[216:219], v[14:17]


	v_mfma_f32_16x16x32_bf16 v[50:53], v[172:175], v[188:191], v[50:53]
	v_mfma_f32_16x16x32_bf16 v[42:45], v[180:183], v[188:191], v[42:45]
	v_mfma_f32_16x16x32_bf16 v[34:37], v[172:175], v[196:199], v[34:37]
	v_mfma_f32_16x16x32_bf16 v[26:29], v[180:183], v[196:199], v[26:29]
	v_mfma_f32_16x16x32_bf16 v[18:21], v[172:175], v[204:207], v[18:21]
	v_mfma_f32_16x16x32_bf16 v[10:13], v[180:183], v[204:207], v[10:13]
	v_mfma_f32_16x16x32_bf16 v[6:9], v[172:175], v[212:215], v[6:9]
	v_mfma_f32_16x16x32_bf16 v[2:5], v[180:183], v[212:215], v[2:5]
	v_mfma_f32_16x16x32_bf16 v[50:53], v[176:179], v[192:195], v[50:53]
	v_mfma_f32_16x16x32_bf16 v[42:45], v[184:187], v[192:195], v[42:45]
	v_mfma_f32_16x16x32_bf16 v[34:37], v[176:179], v[200:203], v[34:37]
	v_mfma_f32_16x16x32_bf16 v[26:29], v[184:187], v[200:203], v[26:29]
	v_mfma_f32_16x16x32_bf16 v[18:21], v[176:179], v[208:211], v[18:21]
	v_mfma_f32_16x16x32_bf16 v[10:13], v[184:187], v[208:211], v[10:13]
	v_mfma_f32_16x16x32_bf16 v[6:9], v[176:179], v[216:219], v[6:9]
	v_mfma_f32_16x16x32_bf16 v[2:5], v[184:187], v[216:219], v[2:5]

	s_barrier
	s_add_i32 s63, 0, 0x18000
	v_add_u32_e32 v155, s63, v150
	s_add_i32 s64, 0, 0x1c000
	ds_read_b128 v[156:159], v155
	ds_read_b128 v[160:163], v155 offset:1024
	ds_read_b128 v[164:167], v155 offset:2048
	ds_read_b128 v[168:171], v155 offset:3072
	v_add_u32_e32 v155, s64, v150
	ds_read_b128 v[172:175], v155
	ds_read_b128 v[176:179], v155 offset:1024
	ds_read_b128 v[180:183], v155 offset:2048
	ds_read_b128 v[184:187], v155 offset:3072
	s_add_u32 s38, s38, 0x20000
	s_addc_u32 s39, s39, 0
	s_mov_b32 m0, s47
	v_lshl_add_u64 v[226:227], s[38:39], 0, v[130:131]
	ds_read_b128 v[188:191], v154 offset:32768
	ds_read_b128 v[192:195], v154 offset:33792
	ds_read_b128 v[196:199], v154 offset:34816
	ds_read_b128 v[200:203], v154 offset:35840
	ds_read_b128 v[204:207], v154 offset:36864
	ds_read_b128 v[208:211], v154 offset:37888
	ds_read_b128 v[212:215], v154 offset:38912
	ds_read_b128 v[216:219], v154 offset:39936
	global_load_lds_dwordx4 v[226:227], off
	v_lshl_add_u64 v[226:227], s[38:39], 0, v[134:135]
	s_mov_b32 m0, s48
	s_nop 0
	global_load_lds_dwordx4 v[226:227], off
	s_waitcnt vmcnt(8)
	s_waitcnt lgkmcnt(0)
	s_barrier

	s_waitcnt lgkmcnt(0)
	v_mfma_f32_16x16x32_bf16 v[126:129], v[156:159], v[188:191], v[126:129]
	v_mfma_f32_16x16x32_bf16 v[122:125], v[164:167], v[188:191], v[122:125]
	v_mfma_f32_16x16x32_bf16 v[118:121], v[156:159], v[196:199], v[118:121]
	v_mfma_f32_16x16x32_bf16 v[110:113], v[164:167], v[196:199], v[110:113]
	v_mfma_f32_16x16x32_bf16 v[102:105], v[156:159], v[204:207], v[102:105]
	v_mfma_f32_16x16x32_bf16 v[94:97], v[164:167], v[204:207], v[94:97]
	v_mfma_f32_16x16x32_bf16 v[86:89], v[156:159], v[212:215], v[86:89]
	v_mfma_f32_16x16x32_bf16 v[78:81], v[164:167], v[212:215], v[78:81]
	v_mfma_f32_16x16x32_bf16 v[126:129], v[160:163], v[192:195], v[126:129]
	v_mfma_f32_16x16x32_bf16 v[122:125], v[168:171], v[192:195], v[122:125]
	v_mfma_f32_16x16x32_bf16 v[118:121], v[160:163], v[200:203], v[118:121]
	v_mfma_f32_16x16x32_bf16 v[110:113], v[168:171], v[200:203], v[110:113]
	v_mfma_f32_16x16x32_bf16 v[102:105], v[160:163], v[208:211], v[102:105]
	v_mfma_f32_16x16x32_bf16 v[94:97], v[168:171], v[208:211], v[94:97]
	v_mfma_f32_16x16x32_bf16 v[86:89], v[160:163], v[216:219], v[86:89]
	v_mfma_f32_16x16x32_bf16 v[78:81], v[168:171], v[216:219], v[78:81]


	v_mfma_f32_16x16x32_bf16 v[114:117], v[172:175], v[188:191], v[114:117]
	v_mfma_f32_16x16x32_bf16 v[106:109], v[180:183], v[188:191], v[106:109]
	v_mfma_f32_16x16x32_bf16 v[98:101], v[172:175], v[196:199], v[98:101]
	v_mfma_f32_16x16x32_bf16 v[90:93], v[180:183], v[196:199], v[90:93]
	v_mfma_f32_16x16x32_bf16 v[82:85], v[172:175], v[204:207], v[82:85]
	v_mfma_f32_16x16x32_bf16 v[74:77], v[180:183], v[204:207], v[74:77]
	v_mfma_f32_16x16x32_bf16 v[70:73], v[172:175], v[212:215], v[70:73]
	v_mfma_f32_16x16x32_bf16 v[66:69], v[180:183], v[212:215], v[66:69]
	v_mfma_f32_16x16x32_bf16 v[114:117], v[176:179], v[192:195], v[114:117]
	v_mfma_f32_16x16x32_bf16 v[106:109], v[184:187], v[192:195], v[106:109]
	v_mfma_f32_16x16x32_bf16 v[98:101], v[176:179], v[200:203], v[98:101]
	v_mfma_f32_16x16x32_bf16 v[90:93], v[184:187], v[200:203], v[90:93]
	v_mfma_f32_16x16x32_bf16 v[82:85], v[176:179], v[208:211], v[82:85]
	v_mfma_f32_16x16x32_bf16 v[74:77], v[184:187], v[208:211], v[74:77]
	v_mfma_f32_16x16x32_bf16 v[70:73], v[176:179], v[216:219], v[70:73]
	v_mfma_f32_16x16x32_bf16 v[66:69], v[184:187], v[216:219], v[66:69]

	s_barrier
	s_add_i32 s38, s63, s43
	v_lshl_add_u64 v[146:147], v[146:147], 0, s[8:9]
	s_mov_b32 m0, s38
	ds_read_b128 v[188:191], v154 offset:49152
	ds_read_b128 v[192:195], v154 offset:50176
	ds_read_b128 v[196:199], v154 offset:51200
	ds_read_b128 v[200:203], v154 offset:52224
	ds_read_b128 v[204:207], v154 offset:53248
	ds_read_b128 v[208:211], v154 offset:54272
	ds_read_b128 v[212:215], v154 offset:55296
	ds_read_b128 v[216:219], v154 offset:56320
	global_load_lds_dwordx4 v[146:147], off
	s_add_i32 m0, s38, 0x2000
	s_add_u32 s36, s36, 0x80080
	v_lshl_add_u64 v[146:147], v[220:221], 0, s[8:9]
	s_addc_u32 s37, s37, 0
	s_add_i32 s38, s64, s43
	global_load_lds_dwordx4 v[146:147], off
	v_lshl_add_u64 v[146:147], s[36:37], 0, v[132:133]
	s_mov_b32 m0, s38
	s_nop 0
	global_load_lds_dwordx4 v[146:147], off
	v_lshl_add_u64 v[146:147], s[36:37], 0, v[136:137]
	s_add_i32 m0, s38, 0x2000
	s_nop 0
	global_load_lds_dwordx4 v[146:147], off
	v_lshl_add_u64 v[146:147], v[222:223], 0, s[8:9]
	s_mov_b32 m0, s50
	s_nop 0
	global_load_lds_dwordx4 v[146:147], off
	v_lshl_add_u64 v[146:147], v[224:225], 0, s[8:9]
	s_mov_b32 m0, s51
	s_nop 0
	global_load_lds_dwordx4 v[146:147], off
	s_waitcnt vmcnt(8)
	s_waitcnt lgkmcnt(0)
	s_barrier

	s_waitcnt lgkmcnt(0)
	v_mfma_f32_16x16x32_bf16 v[62:65], v[156:159], v[188:191], v[62:65]
	v_mfma_f32_16x16x32_bf16 v[58:61], v[164:167], v[188:191], v[58:61]
	v_mfma_f32_16x16x32_bf16 v[54:57], v[156:159], v[196:199], v[54:57]
	v_mfma_f32_16x16x32_bf16 v[46:49], v[164:167], v[196:199], v[46:49]
	v_mfma_f32_16x16x32_bf16 v[38:41], v[156:159], v[204:207], v[38:41]
	v_mfma_f32_16x16x32_bf16 v[30:33], v[164:167], v[204:207], v[30:33]
	v_mfma_f32_16x16x32_bf16 v[22:25], v[156:159], v[212:215], v[22:25]
	v_mfma_f32_16x16x32_bf16 v[14:17], v[164:167], v[212:215], v[14:17]
	v_mfma_f32_16x16x32_bf16 v[62:65], v[160:163], v[192:195], v[62:65]
	v_mfma_f32_16x16x32_bf16 v[58:61], v[168:171], v[192:195], v[58:61]
	v_mfma_f32_16x16x32_bf16 v[54:57], v[160:163], v[200:203], v[54:57]
	v_mfma_f32_16x16x32_bf16 v[46:49], v[168:171], v[200:203], v[46:49]
	v_mfma_f32_16x16x32_bf16 v[38:41], v[160:163], v[208:211], v[38:41]
	v_mfma_f32_16x16x32_bf16 v[30:33], v[168:171], v[208:211], v[30:33]
	v_mfma_f32_16x16x32_bf16 v[22:25], v[160:163], v[216:219], v[22:25]
	v_mfma_f32_16x16x32_bf16 v[14:17], v[168:171], v[216:219], v[14:17]


	v_mfma_f32_16x16x32_bf16 v[50:53], v[172:175], v[188:191], v[50:53]
	v_mfma_f32_16x16x32_bf16 v[42:45], v[180:183], v[188:191], v[42:45]
	v_mfma_f32_16x16x32_bf16 v[34:37], v[172:175], v[196:199], v[34:37]
	v_mfma_f32_16x16x32_bf16 v[26:29], v[180:183], v[196:199], v[26:29]
	v_mfma_f32_16x16x32_bf16 v[18:21], v[172:175], v[204:207], v[18:21]
	v_mfma_f32_16x16x32_bf16 v[10:13], v[180:183], v[204:207], v[10:13]
	v_mfma_f32_16x16x32_bf16 v[6:9], v[172:175], v[212:215], v[6:9]
	v_mfma_f32_16x16x32_bf16 v[2:5], v[180:183], v[212:215], v[2:5]
	v_mfma_f32_16x16x32_bf16 v[50:53], v[176:179], v[192:195], v[50:53]
	v_mfma_f32_16x16x32_bf16 v[42:45], v[184:187], v[192:195], v[42:45]
	v_mfma_f32_16x16x32_bf16 v[34:37], v[176:179], v[200:203], v[34:37]
	v_mfma_f32_16x16x32_bf16 v[26:29], v[184:187], v[200:203], v[26:29]
	v_mfma_f32_16x16x32_bf16 v[18:21], v[176:179], v[208:211], v[18:21]
	v_mfma_f32_16x16x32_bf16 v[10:13], v[184:187], v[208:211], v[10:13]
	v_mfma_f32_16x16x32_bf16 v[6:9], v[176:179], v[216:219], v[6:9]
	v_mfma_f32_16x16x32_bf16 v[2:5], v[184:187], v[216:219], v[2:5]

	s_barrier
	s_add_i32 s62, s62, 2
	s_add_u32 s0, s0, 0x100
	s_addc_u32 s1, s1, 0
	s_add_u32 s60, s60, 0x100
	s_addc_u32 s61, s61, 0
	s_cmp_gt_u32 s62, 5
	s_cbranch_scc0 .LBB0_207
	s_and_b64 vcc, exec, s[10:11]
	s_cbranch_vccz .LBB0_210
	s_barrier

.LBB0_290:
	s_add_u32 s12, s60, s10
	s_addc_u32 s13, s61, s11
	s_add_u32 s12, s12, 0x100
	s_addc_u32 s13, s13, 0
	s_add_u32 s97, s28, s10
	s_addc_u32 vcc_lo, s29, s11
	s_add_i32 vcc_hi, 0, 0x10000
	s_cmpk_eq_i32 s10, 0xf00
	s_cselect_b32 s41, s63, s13
	s_cselect_b32 s40, s94, s12
	v_add_u32_e32 v154, vcc_hi, v169
	s_cselect_b32 s13, s67, vcc_lo
	s_cselect_b32 s12, s95, s97
	s_add_i32 s97, 0, 0x14000
	ds_read_b128 v[146:149], v154
	ds_read_b128 v[150:153], v154 offset:1024
	ds_read_b128 v[164:167], v154 offset:2048
	ds_read_b128 v[172:175], v154 offset:3072
	v_add_u32_e32 v154, s97, v169
	ds_read_b128 v[176:179], v154
	ds_read_b128 v[180:183], v154 offset:1024
	ds_read_b128 v[184:187], v154 offset:2048
	ds_read_b128 v[188:191], v154 offset:3072
	v_lshl_add_u64 v[196:197], v[142:143], 0, s[10:11]
	s_add_i32 m0, s81, 0xc000
	ds_read_b128 v[200:203], v171
	ds_read_b128 v[204:207], v171 offset:1024
	ds_read_b128 v[208:211], v171 offset:2048
	ds_read_b128 v[212:215], v171 offset:3072
	ds_read_b128 v[216:219], v171 offset:4096
	ds_read_b128 v[220:223], v171 offset:5120
	ds_read_b128 v[224:227], v171 offset:6144
	ds_read_b128 v[228:231], v171 offset:7168
	global_load_lds_dwordx4 v[196:197], off
	v_lshl_add_u64 v[196:197], v[144:145], 0, s[10:11]
	s_add_i32 m0, s81, 0xe000
	s_nop 0
	global_load_lds_dwordx4 v[196:197], off
	s_waitcnt vmcnt(8)
	s_waitcnt lgkmcnt(0)
	s_barrier

	s_waitcnt lgkmcnt(0)
	v_mfma_f32_16x16x32_bf16 v[126:129], v[146:149], v[200:203], v[126:129]
	v_mfma_f32_16x16x32_bf16 v[122:125], v[164:167], v[200:203], v[122:125]
	v_mfma_f32_16x16x32_bf16 v[118:121], v[146:149], v[208:211], v[118:121]
	v_mfma_f32_16x16x32_bf16 v[114:117], v[164:167], v[208:211], v[114:117]
	v_mfma_f32_16x16x32_bf16 v[110:113], v[146:149], v[216:219], v[110:113]
	v_mfma_f32_16x16x32_bf16 v[106:109], v[164:167], v[216:219], v[106:109]
	v_mfma_f32_16x16x32_bf16 v[102:105], v[146:149], v[224:227], v[102:105]
	v_mfma_f32_16x16x32_bf16 v[98:101], v[164:167], v[224:227], v[98:101]
	v_mfma_f32_16x16x32_bf16 v[126:129], v[150:153], v[204:207], v[126:129]
	v_mfma_f32_16x16x32_bf16 v[122:125], v[172:175], v[204:207], v[122:125]
	v_mfma_f32_16x16x32_bf16 v[118:121], v[150:153], v[212:215], v[118:121]
	v_mfma_f32_16x16x32_bf16 v[114:117], v[172:175], v[212:215], v[114:117]
	v_mfma_f32_16x16x32_bf16 v[110:113], v[150:153], v[220:223], v[110:113]
	v_mfma_f32_16x16x32_bf16 v[106:109], v[172:175], v[220:223], v[106:109]
	v_mfma_f32_16x16x32_bf16 v[102:105], v[150:153], v[228:231], v[102:105]
	v_mfma_f32_16x16x32_bf16 v[98:101], v[172:175], v[228:231], v[98:101]


	v_mfma_f32_16x16x32_bf16 v[94:97], v[176:179], v[200:203], v[94:97]
	v_mfma_f32_16x16x32_bf16 v[90:93], v[184:187], v[200:203], v[90:93]
	v_mfma_f32_16x16x32_bf16 v[86:89], v[176:179], v[208:211], v[86:89]
	v_mfma_f32_16x16x32_bf16 v[82:85], v[184:187], v[208:211], v[82:85]
	v_mfma_f32_16x16x32_bf16 v[78:81], v[176:179], v[216:219], v[78:81]
	v_mfma_f32_16x16x32_bf16 v[74:77], v[184:187], v[216:219], v[74:77]
	v_mfma_f32_16x16x32_bf16 v[70:73], v[176:179], v[224:227], v[70:73]
	v_mfma_f32_16x16x32_bf16 v[66:69], v[184:187], v[224:227], v[66:69]
	v_mfma_f32_16x16x32_bf16 v[94:97], v[180:183], v[204:207], v[94:97]
	v_mfma_f32_16x16x32_bf16 v[90:93], v[188:191], v[204:207], v[90:93]
	v_mfma_f32_16x16x32_bf16 v[86:89], v[180:183], v[212:215], v[86:89]
	v_mfma_f32_16x16x32_bf16 v[82:85], v[188:191], v[212:215], v[82:85]
	v_mfma_f32_16x16x32_bf16 v[78:81], v[180:183], v[220:223], v[78:81]
	v_mfma_f32_16x16x32_bf16 v[74:77], v[188:191], v[220:223], v[74:77]
	v_mfma_f32_16x16x32_bf16 v[70:73], v[180:183], v[228:231], v[70:73]
	v_mfma_f32_16x16x32_bf16 v[66:69], v[188:191], v[228:231], v[66:69]

	s_barrier
	s_add_i32 vcc_lo, vcc_hi, s80
	v_lshl_add_u64 v[196:197], s[12:13], 0, v[132:133]
	s_mov_b32 m0, vcc_lo
	ds_read_b128 v[200:203], v171 offset:16384
	ds_read_b128 v[204:207], v171 offset:17408
	ds_read_b128 v[208:211], v171 offset:18432
	ds_read_b128 v[212:215], v171 offset:19456
	ds_read_b128 v[216:219], v171 offset:20480
	ds_read_b128 v[220:223], v171 offset:21504
	ds_read_b128 v[224:227], v171 offset:22528
	ds_read_b128 v[228:231], v171 offset:23552
	global_load_lds_dwordx4 v[196:197], off
	s_add_i32 m0, vcc_lo, 0x2000
	s_add_u32 vcc_lo, s12, 0x80000
	v_lshl_add_u64 v[232:233], s[12:13], 0, v[136:137]
	s_addc_u32 vcc_hi, s13, 0
	s_add_i32 s97, s97, s80
	global_load_lds_dwordx4 v[232:233], off
	v_lshl_add_u64 v[234:235], vcc, 0, v[132:133]
	s_mov_b32 m0, s97
	v_lshl_add_u64 v[236:237], s[40:41], 0, v[134:135]
	global_load_lds_dwordx4 v[234:235], off
	v_lshl_add_u64 v[234:235], vcc, 0, v[136:137]
	s_add_i32 m0, s97, 0x2000
	s_nop 0
	global_load_lds_dwordx4 v[234:235], off
	v_lshl_add_u64 v[234:235], s[40:41], 0, v[130:131]
	s_mov_b32 m0, s81
	s_nop 0
	global_load_lds_dwordx4 v[234:235], off
	s_mov_b32 m0, s82
	s_nop 0
	global_load_lds_dwordx4 v[236:237], off
	s_waitcnt vmcnt(8)
	s_waitcnt lgkmcnt(0)
	s_barrier

	s_waitcnt lgkmcnt(0)
	v_mfma_f32_16x16x32_bf16 v[62:65], v[146:149], v[200:203], v[62:65]
	v_mfma_f32_16x16x32_bf16 v[58:61], v[164:167], v[200:203], v[58:61]
	v_mfma_f32_16x16x32_bf16 v[54:57], v[146:149], v[208:211], v[54:57]
	v_mfma_f32_16x16x32_bf16 v[50:53], v[164:167], v[208:211], v[50:53]
	v_mfma_f32_16x16x32_bf16 v[46:49], v[146:149], v[216:219], v[46:49]
	v_mfma_f32_16x16x32_bf16 v[42:45], v[164:167], v[216:219], v[42:45]
	v_mfma_f32_16x16x32_bf16 v[38:41], v[146:149], v[224:227], v[38:41]
	v_mfma_f32_16x16x32_bf16 v[34:37], v[164:167], v[224:227], v[34:37]
	v_mfma_f32_16x16x32_bf16 v[62:65], v[150:153], v[204:207], v[62:65]
	v_mfma_f32_16x16x32_bf16 v[58:61], v[172:175], v[204:207], v[58:61]
	v_mfma_f32_16x16x32_bf16 v[54:57], v[150:153], v[212:215], v[54:57]
	v_mfma_f32_16x16x32_bf16 v[50:53], v[172:175], v[212:215], v[50:53]
	v_mfma_f32_16x16x32_bf16 v[46:49], v[150:153], v[220:223], v[46:49]
	v_mfma_f32_16x16x32_bf16 v[42:45], v[172:175], v[220:223], v[42:45]
	v_mfma_f32_16x16x32_bf16 v[38:41], v[150:153], v[228:231], v[38:41]
	v_mfma_f32_16x16x32_bf16 v[34:37], v[172:175], v[228:231], v[34:37]


	v_mfma_f32_16x16x32_bf16 v[30:33], v[176:179], v[200:203], v[30:33]
	v_mfma_f32_16x16x32_bf16 v[26:29], v[184:187], v[200:203], v[26:29]
	v_mfma_f32_16x16x32_bf16 v[22:25], v[176:179], v[208:211], v[22:25]
	v_mfma_f32_16x16x32_bf16 v[18:21], v[184:187], v[208:211], v[18:21]
	v_mfma_f32_16x16x32_bf16 v[14:17], v[176:179], v[216:219], v[14:17]
	v_mfma_f32_16x16x32_bf16 v[10:13], v[184:187], v[216:219], v[10:13]
	v_mfma_f32_16x16x32_bf16 v[6:9], v[176:179], v[224:227], v[6:9]
	v_mfma_f32_16x16x32_bf16 v[2:5], v[184:187], v[224:227], v[2:5]
	v_mfma_f32_16x16x32_bf16 v[30:33], v[180:183], v[204:207], v[30:33]
	v_mfma_f32_16x16x32_bf16 v[26:29], v[188:191], v[204:207], v[26:29]
	v_mfma_f32_16x16x32_bf16 v[22:25], v[180:183], v[212:215], v[22:25]
	v_mfma_f32_16x16x32_bf16 v[18:21], v[188:191], v[212:215], v[18:21]
	v_mfma_f32_16x16x32_bf16 v[14:17], v[180:183], v[220:223], v[14:17]
	v_mfma_f32_16x16x32_bf16 v[10:13], v[188:191], v[220:223], v[10:13]
	v_mfma_f32_16x16x32_bf16 v[6:9], v[180:183], v[228:231], v[6:9]
	v_mfma_f32_16x16x32_bf16 v[2:5], v[188:191], v[228:231], v[2:5]

	s_barrier
	s_add_i32 s97, 0, 0x18000
	v_add_u32_e32 v154, s97, v169
	s_add_i32 vcc_lo, 0, 0x1c000
	ds_read_b128 v[146:149], v154
	ds_read_b128 v[150:153], v154 offset:1024
	ds_read_b128 v[164:167], v154 offset:2048
	ds_read_b128 v[172:175], v154 offset:3072
	v_add_u32_e32 v154, vcc_lo, v169
	ds_read_b128 v[176:179], v154
	ds_read_b128 v[180:183], v154 offset:1024
	ds_read_b128 v[184:187], v154 offset:2048
	ds_read_b128 v[188:191], v154 offset:3072
	s_add_u32 s40, s40, 0x80000
	s_addc_u32 s41, s41, 0
	s_mov_b32 m0, s83
	v_lshl_add_u64 v[238:239], s[40:41], 0, v[130:131]
	ds_read_b128 v[200:203], v171 offset:32768
	ds_read_b128 v[204:207], v171 offset:33792
	ds_read_b128 v[208:211], v171 offset:34816
	ds_read_b128 v[212:215], v171 offset:35840
	ds_read_b128 v[216:219], v171 offset:36864
	ds_read_b128 v[220:223], v171 offset:37888
	ds_read_b128 v[224:227], v171 offset:38912
	ds_read_b128 v[228:231], v171 offset:39936
	global_load_lds_dwordx4 v[238:239], off
	v_lshl_add_u64 v[238:239], s[40:41], 0, v[134:135]
	s_mov_b32 m0, s84
	s_nop 0
	global_load_lds_dwordx4 v[238:239], off
	s_waitcnt vmcnt(8)
	s_waitcnt lgkmcnt(0)
	s_barrier

	s_waitcnt lgkmcnt(0)
	v_mfma_f32_16x16x32_bf16 v[126:129], v[146:149], v[200:203], v[126:129]
	v_mfma_f32_16x16x32_bf16 v[122:125], v[164:167], v[200:203], v[122:125]
	v_mfma_f32_16x16x32_bf16 v[118:121], v[146:149], v[208:211], v[118:121]
	v_mfma_f32_16x16x32_bf16 v[114:117], v[164:167], v[208:211], v[114:117]
	v_mfma_f32_16x16x32_bf16 v[110:113], v[146:149], v[216:219], v[110:113]
	v_mfma_f32_16x16x32_bf16 v[106:109], v[164:167], v[216:219], v[106:109]
	v_mfma_f32_16x16x32_bf16 v[102:105], v[146:149], v[224:227], v[102:105]
	v_mfma_f32_16x16x32_bf16 v[98:101], v[164:167], v[224:227], v[98:101]
	v_mfma_f32_16x16x32_bf16 v[126:129], v[150:153], v[204:207], v[126:129]
	v_mfma_f32_16x16x32_bf16 v[122:125], v[172:175], v[204:207], v[122:125]
	v_mfma_f32_16x16x32_bf16 v[118:121], v[150:153], v[212:215], v[118:121]
	v_mfma_f32_16x16x32_bf16 v[114:117], v[172:175], v[212:215], v[114:117]
	v_mfma_f32_16x16x32_bf16 v[110:113], v[150:153], v[220:223], v[110:113]
	v_mfma_f32_16x16x32_bf16 v[106:109], v[172:175], v[220:223], v[106:109]
	v_mfma_f32_16x16x32_bf16 v[102:105], v[150:153], v[228:231], v[102:105]
	v_mfma_f32_16x16x32_bf16 v[98:101], v[172:175], v[228:231], v[98:101]


	v_mfma_f32_16x16x32_bf16 v[94:97], v[176:179], v[200:203], v[94:97]
	v_mfma_f32_16x16x32_bf16 v[90:93], v[184:187], v[200:203], v[90:93]
	v_mfma_f32_16x16x32_bf16 v[86:89], v[176:179], v[208:211], v[86:89]
	v_mfma_f32_16x16x32_bf16 v[82:85], v[184:187], v[208:211], v[82:85]
	v_mfma_f32_16x16x32_bf16 v[78:81], v[176:179], v[216:219], v[78:81]
	v_mfma_f32_16x16x32_bf16 v[74:77], v[184:187], v[216:219], v[74:77]
	v_mfma_f32_16x16x32_bf16 v[70:73], v[176:179], v[224:227], v[70:73]
	v_mfma_f32_16x16x32_bf16 v[66:69], v[184:187], v[224:227], v[66:69]
	v_mfma_f32_16x16x32_bf16 v[94:97], v[180:183], v[204:207], v[94:97]
	v_mfma_f32_16x16x32_bf16 v[90:93], v[188:191], v[204:207], v[90:93]
	v_mfma_f32_16x16x32_bf16 v[86:89], v[180:183], v[212:215], v[86:89]
	v_mfma_f32_16x16x32_bf16 v[82:85], v[188:191], v[212:215], v[82:85]
	v_mfma_f32_16x16x32_bf16 v[78:81], v[180:183], v[220:223], v[78:81]
	v_mfma_f32_16x16x32_bf16 v[74:77], v[188:191], v[220:223], v[74:77]
	v_mfma_f32_16x16x32_bf16 v[70:73], v[180:183], v[228:231], v[70:73]
	v_mfma_f32_16x16x32_bf16 v[66:69], v[188:191], v[228:231], v[66:69]

	s_barrier
	s_add_i32 s40, s97, s80
	v_lshl_add_u64 v[196:197], v[196:197], 0, s[34:35]
	s_mov_b32 m0, s40
	ds_read_b128 v[200:203], v171 offset:49152
	ds_read_b128 v[204:207], v171 offset:50176
	ds_read_b128 v[208:211], v171 offset:51200
	ds_read_b128 v[212:215], v171 offset:52224
	ds_read_b128 v[216:219], v171 offset:53248
	ds_read_b128 v[220:223], v171 offset:54272
	ds_read_b128 v[224:227], v171 offset:55296
	ds_read_b128 v[228:231], v171 offset:56320
	global_load_lds_dwordx4 v[196:197], off
	s_add_i32 m0, s40, 0x2000
	s_add_u32 s12, s12, 0x80080
	v_lshl_add_u64 v[196:197], v[232:233], 0, s[34:35]
	s_addc_u32 s13, s13, 0
	s_add_i32 s40, vcc_lo, s80
	global_load_lds_dwordx4 v[196:197], off
	v_lshl_add_u64 v[196:197], s[12:13], 0, v[132:133]
	s_mov_b32 m0, s40
	s_nop 0
	global_load_lds_dwordx4 v[196:197], off
	v_lshl_add_u64 v[196:197], s[12:13], 0, v[136:137]
	s_add_i32 m0, s40, 0x2000
	s_nop 0
	global_load_lds_dwordx4 v[196:197], off
	v_lshl_add_u64 v[196:197], v[234:235], 0, s[34:35]
	s_mov_b32 m0, s85
	s_nop 0
	global_load_lds_dwordx4 v[196:197], off
	v_lshl_add_u64 v[196:197], v[236:237], 0, s[34:35]
	s_mov_b32 m0, s86
	s_nop 0
	global_load_lds_dwordx4 v[196:197], off
	s_waitcnt vmcnt(8)
	s_waitcnt lgkmcnt(0)
	s_barrier

	s_waitcnt lgkmcnt(0)
	v_mfma_f32_16x16x32_bf16 v[62:65], v[146:149], v[200:203], v[62:65]
	v_mfma_f32_16x16x32_bf16 v[58:61], v[164:167], v[200:203], v[58:61]
	v_mfma_f32_16x16x32_bf16 v[54:57], v[146:149], v[208:211], v[54:57]
	v_mfma_f32_16x16x32_bf16 v[50:53], v[164:167], v[208:211], v[50:53]
	v_mfma_f32_16x16x32_bf16 v[46:49], v[146:149], v[216:219], v[46:49]
	v_mfma_f32_16x16x32_bf16 v[42:45], v[164:167], v[216:219], v[42:45]
	v_mfma_f32_16x16x32_bf16 v[38:41], v[146:149], v[224:227], v[38:41]
	v_mfma_f32_16x16x32_bf16 v[34:37], v[164:167], v[224:227], v[34:37]
	v_mfma_f32_16x16x32_bf16 v[62:65], v[150:153], v[204:207], v[62:65]
	v_mfma_f32_16x16x32_bf16 v[58:61], v[172:175], v[204:207], v[58:61]
	v_mfma_f32_16x16x32_bf16 v[54:57], v[150:153], v[212:215], v[54:57]
	v_mfma_f32_16x16x32_bf16 v[50:53], v[172:175], v[212:215], v[50:53]
	v_mfma_f32_16x16x32_bf16 v[46:49], v[150:153], v[220:223], v[46:49]
	v_mfma_f32_16x16x32_bf16 v[42:45], v[172:175], v[220:223], v[42:45]
	v_mfma_f32_16x16x32_bf16 v[38:41], v[150:153], v[228:231], v[38:41]
	v_mfma_f32_16x16x32_bf16 v[34:37], v[172:175], v[228:231], v[34:37]


	v_mfma_f32_16x16x32_bf16 v[30:33], v[176:179], v[200:203], v[30:33]
	v_mfma_f32_16x16x32_bf16 v[26:29], v[184:187], v[200:203], v[26:29]
	v_mfma_f32_16x16x32_bf16 v[22:25], v[176:179], v[208:211], v[22:25]
	v_mfma_f32_16x16x32_bf16 v[18:21], v[184:187], v[208:211], v[18:21]
	v_mfma_f32_16x16x32_bf16 v[14:17], v[176:179], v[216:219], v[14:17]
	v_mfma_f32_16x16x32_bf16 v[10:13], v[184:187], v[216:219], v[10:13]
	v_mfma_f32_16x16x32_bf16 v[6:9], v[176:179], v[224:227], v[6:9]
	v_mfma_f32_16x16x32_bf16 v[2:5], v[184:187], v[224:227], v[2:5]
	v_mfma_f32_16x16x32_bf16 v[30:33], v[180:183], v[204:207], v[30:33]
	v_mfma_f32_16x16x32_bf16 v[26:29], v[188:191], v[204:207], v[26:29]
	v_mfma_f32_16x16x32_bf16 v[22:25], v[180:183], v[212:215], v[22:25]
	v_mfma_f32_16x16x32_bf16 v[18:21], v[188:191], v[212:215], v[18:21]
	v_mfma_f32_16x16x32_bf16 v[14:17], v[180:183], v[220:223], v[14:17]
	v_mfma_f32_16x16x32_bf16 v[10:13], v[188:191], v[220:223], v[10:13]
	v_mfma_f32_16x16x32_bf16 v[6:9], v[180:183], v[228:231], v[6:9]
	v_mfma_f32_16x16x32_bf16 v[2:5], v[188:191], v[228:231], v[2:5]

	s_barrier
	s_add_i32 s96, s96, 2
	s_add_u32 s10, s10, 0x100
	s_addc_u32 s11, s11, 0
	s_cmp_gt_u32 s96, 29
	s_cbranch_scc0 .LBB0_290
	s_and_b64 vcc, exec, s[56:57]
	s_cbranch_vccz .LBB0_293
	s_barrier

.LBB0_473:
	s_add_u32 s64, s56, s10
	s_addc_u32 s65, s57, s11
	s_add_u32 s64, s64, 0x100
	s_addc_u32 s65, s65, 0
	s_add_u32 vcc_lo, s93, s10
	s_addc_u32 vcc_hi, s94, s11
	s_add_i32 s16, 0, 0x10000
	s_cmpk_eq_i32 s10, 0xf00
	s_cselect_b32 s67, s55, s65
	s_cselect_b32 s66, s95, s64
	s_cselect_b32 s65, s53, vcc_hi
	s_cselect_b32 s64, s96, vcc_lo
	s_add_i32 s24, 0, 0x14000
	v_add_u32_e32 v146, s16, v197
	v_add_u32_e32 v182, s24, v197
	ds_read_b128 v[134:137], v146
	ds_read_b128 v[138:141], v146 offset:1024
	ds_read_b128 v[142:145], v146 offset:2048
	ds_read_b128 v[146:149], v146 offset:3072
	ds_read_b128 v[150:153], v182
	ds_read_b128 v[174:177], v182 offset:1024
	ds_read_b128 v[178:181], v182 offset:2048
	ds_read_b128 v[182:185], v182 offset:3072
	v_lshl_add_u64 v[190:191], v[130:131], 0, s[10:11]
	s_add_i32 m0, s80, 0xc000
	ds_read_b128 v[186:189], v200
	ds_read_b128 v[202:205], v200 offset:1024
	ds_read_b128 v[206:209], v200 offset:2048
	ds_read_b128 v[210:213], v200 offset:3072
	ds_read_b128 v[214:217], v200 offset:4096
	ds_read_b128 v[218:221], v200 offset:5120
	ds_read_b128 v[222:225], v200 offset:6144
	ds_read_b128 v[226:229], v200 offset:7168
	global_load_lds_dwordx4 v[190:191], off
	v_lshl_add_u64 v[190:191], v[132:133], 0, s[10:11]
	s_add_i32 m0, s80, 0xe000
	s_nop 0
	global_load_lds_dwordx4 v[190:191], off
	s_waitcnt vmcnt(8)
	s_waitcnt lgkmcnt(0)
	s_barrier

	s_waitcnt lgkmcnt(0)
	v_mfma_f32_16x16x32_bf16 v[126:129], v[134:137], v[186:189], v[126:129]
	v_mfma_f32_16x16x32_bf16 v[122:125], v[142:145], v[186:189], v[122:125]
	v_mfma_f32_16x16x32_bf16 v[118:121], v[134:137], v[206:209], v[118:121]
	v_mfma_f32_16x16x32_bf16 v[114:117], v[142:145], v[206:209], v[114:117]
	v_mfma_f32_16x16x32_bf16 v[110:113], v[134:137], v[214:217], v[110:113]
	v_mfma_f32_16x16x32_bf16 v[106:109], v[142:145], v[214:217], v[106:109]
	v_mfma_f32_16x16x32_bf16 v[102:105], v[134:137], v[222:225], v[102:105]
	v_mfma_f32_16x16x32_bf16 v[98:101], v[142:145], v[222:225], v[98:101]
	v_mfma_f32_16x16x32_bf16 v[126:129], v[138:141], v[202:205], v[126:129]
	v_mfma_f32_16x16x32_bf16 v[122:125], v[146:149], v[202:205], v[122:125]
	v_mfma_f32_16x16x32_bf16 v[118:121], v[138:141], v[210:213], v[118:121]
	v_mfma_f32_16x16x32_bf16 v[114:117], v[146:149], v[210:213], v[114:117]
	v_mfma_f32_16x16x32_bf16 v[110:113], v[138:141], v[218:221], v[110:113]
	v_mfma_f32_16x16x32_bf16 v[106:109], v[146:149], v[218:221], v[106:109]
	v_mfma_f32_16x16x32_bf16 v[102:105], v[138:141], v[226:229], v[102:105]
	v_mfma_f32_16x16x32_bf16 v[98:101], v[146:149], v[226:229], v[98:101]


	v_mfma_f32_16x16x32_bf16 v[94:97], v[150:153], v[186:189], v[94:97]
	v_mfma_f32_16x16x32_bf16 v[90:93], v[178:181], v[186:189], v[90:93]
	v_mfma_f32_16x16x32_bf16 v[86:89], v[150:153], v[206:209], v[86:89]
	v_mfma_f32_16x16x32_bf16 v[82:85], v[178:181], v[206:209], v[82:85]
	v_mfma_f32_16x16x32_bf16 v[78:81], v[150:153], v[214:217], v[78:81]
	v_mfma_f32_16x16x32_bf16 v[74:77], v[178:181], v[214:217], v[74:77]
	v_mfma_f32_16x16x32_bf16 v[70:73], v[150:153], v[222:225], v[70:73]
	v_mfma_f32_16x16x32_bf16 v[66:69], v[178:181], v[222:225], v[66:69]
	v_mfma_f32_16x16x32_bf16 v[94:97], v[174:177], v[202:205], v[94:97]
	v_mfma_f32_16x16x32_bf16 v[90:93], v[182:185], v[202:205], v[90:93]
	v_mfma_f32_16x16x32_bf16 v[86:89], v[174:177], v[210:213], v[86:89]
	v_mfma_f32_16x16x32_bf16 v[82:85], v[182:185], v[210:213], v[82:85]
	v_mfma_f32_16x16x32_bf16 v[78:81], v[174:177], v[218:221], v[78:81]
	v_mfma_f32_16x16x32_bf16 v[74:77], v[182:185], v[218:221], v[74:77]
	v_mfma_f32_16x16x32_bf16 v[70:73], v[174:177], v[226:229], v[70:73]
	v_mfma_f32_16x16x32_bf16 v[66:69], v[182:185], v[226:229], v[66:69]

	s_barrier
	s_add_i32 s16, s16, s30
	v_lshl_add_u64 v[190:191], s[64:65], 0, v[154:155]
	s_mov_b32 m0, s16
	ds_read_b128 v[186:189], v200 offset:16384
	ds_read_b128 v[202:205], v200 offset:17408
	ds_read_b128 v[206:209], v200 offset:18432
	ds_read_b128 v[210:213], v200 offset:19456
	ds_read_b128 v[214:217], v200 offset:20480
	ds_read_b128 v[218:221], v200 offset:21504
	ds_read_b128 v[222:225], v200 offset:22528
	ds_read_b128 v[226:229], v200 offset:23552
	global_load_lds_dwordx4 v[190:191], off
	s_add_i32 m0, s16, 0x2000
	s_add_u32 vcc_lo, s64, 0x80000
	v_lshl_add_u64 v[230:231], s[64:65], 0, v[164:165]
	s_addc_u32 vcc_hi, s65, 0
	s_add_i32 s16, s24, s30
	global_load_lds_dwordx4 v[230:231], off
	v_lshl_add_u64 v[232:233], vcc, 0, v[154:155]
	s_mov_b32 m0, s16
	v_lshl_add_u64 v[234:235], s[66:67], 0, v[166:167]
	global_load_lds_dwordx4 v[232:233], off
	v_lshl_add_u64 v[232:233], vcc, 0, v[164:165]
	s_add_i32 m0, s16, 0x2000
	s_nop 0
	global_load_lds_dwordx4 v[232:233], off
	v_lshl_add_u64 v[232:233], s[66:67], 0, v[168:169]
	s_mov_b32 m0, s80
	s_nop 0
	global_load_lds_dwordx4 v[232:233], off
	s_mov_b32 m0, s81
	s_nop 0
	global_load_lds_dwordx4 v[234:235], off
	s_waitcnt vmcnt(8)
	s_waitcnt lgkmcnt(0)
	s_barrier

	s_waitcnt lgkmcnt(0)
	v_mfma_f32_16x16x32_bf16 v[62:65], v[134:137], v[186:189], v[62:65]
	v_mfma_f32_16x16x32_bf16 v[58:61], v[142:145], v[186:189], v[58:61]
	v_mfma_f32_16x16x32_bf16 v[54:57], v[134:137], v[206:209], v[54:57]
	v_mfma_f32_16x16x32_bf16 v[50:53], v[142:145], v[206:209], v[50:53]
	v_mfma_f32_16x16x32_bf16 v[46:49], v[134:137], v[214:217], v[46:49]
	v_mfma_f32_16x16x32_bf16 v[42:45], v[142:145], v[214:217], v[42:45]
	v_mfma_f32_16x16x32_bf16 v[38:41], v[134:137], v[222:225], v[38:41]
	v_mfma_f32_16x16x32_bf16 v[34:37], v[142:145], v[222:225], v[34:37]
	v_mfma_f32_16x16x32_bf16 v[62:65], v[138:141], v[202:205], v[62:65]
	v_mfma_f32_16x16x32_bf16 v[58:61], v[146:149], v[202:205], v[58:61]
	v_mfma_f32_16x16x32_bf16 v[54:57], v[138:141], v[210:213], v[54:57]
	v_mfma_f32_16x16x32_bf16 v[50:53], v[146:149], v[210:213], v[50:53]
	v_mfma_f32_16x16x32_bf16 v[46:49], v[138:141], v[218:221], v[46:49]
	v_mfma_f32_16x16x32_bf16 v[42:45], v[146:149], v[218:221], v[42:45]
	v_mfma_f32_16x16x32_bf16 v[38:41], v[138:141], v[226:229], v[38:41]
	v_mfma_f32_16x16x32_bf16 v[34:37], v[146:149], v[226:229], v[34:37]


	v_mfma_f32_16x16x32_bf16 v[30:33], v[150:153], v[186:189], v[30:33]
	v_mfma_f32_16x16x32_bf16 v[26:29], v[178:181], v[186:189], v[26:29]
	v_mfma_f32_16x16x32_bf16 v[22:25], v[150:153], v[206:209], v[22:25]
	v_mfma_f32_16x16x32_bf16 v[18:21], v[178:181], v[206:209], v[18:21]
	v_mfma_f32_16x16x32_bf16 v[14:17], v[150:153], v[214:217], v[14:17]
	v_mfma_f32_16x16x32_bf16 v[10:13], v[178:181], v[214:217], v[10:13]
	v_mfma_f32_16x16x32_bf16 v[6:9], v[150:153], v[222:225], v[6:9]
	v_mfma_f32_16x16x32_bf16 v[2:5], v[178:181], v[222:225], v[2:5]
	v_mfma_f32_16x16x32_bf16 v[30:33], v[174:177], v[202:205], v[30:33]
	v_mfma_f32_16x16x32_bf16 v[26:29], v[182:185], v[202:205], v[26:29]
	v_mfma_f32_16x16x32_bf16 v[22:25], v[174:177], v[210:213], v[22:25]
	v_mfma_f32_16x16x32_bf16 v[18:21], v[182:185], v[210:213], v[18:21]
	v_mfma_f32_16x16x32_bf16 v[14:17], v[174:177], v[218:221], v[14:17]
	v_mfma_f32_16x16x32_bf16 v[10:13], v[182:185], v[218:221], v[10:13]
	v_mfma_f32_16x16x32_bf16 v[6:9], v[174:177], v[226:229], v[6:9]
	v_mfma_f32_16x16x32_bf16 v[2:5], v[182:185], v[226:229], v[2:5]

	s_barrier
	s_add_i32 s16, 0, 0x18000
	s_add_i32 s24, 0, 0x1c000
	v_add_u32_e32 v146, s16, v197
	v_add_u32_e32 v182, s24, v197
	ds_read_b128 v[134:137], v146
	ds_read_b128 v[138:141], v146 offset:1024
	ds_read_b128 v[142:145], v146 offset:2048
	ds_read_b128 v[146:149], v146 offset:3072
	ds_read_b128 v[150:153], v182
	ds_read_b128 v[174:177], v182 offset:1024
	ds_read_b128 v[178:181], v182 offset:2048
	ds_read_b128 v[182:185], v182 offset:3072
	s_add_u32 s66, s66, 0x80000
	s_addc_u32 s67, s67, 0
	s_mov_b32 m0, s82
	v_lshl_add_u64 v[236:237], s[66:67], 0, v[168:169]
	ds_read_b128 v[186:189], v200 offset:32768
	ds_read_b128 v[202:205], v200 offset:33792
	ds_read_b128 v[206:209], v200 offset:34816
	ds_read_b128 v[210:213], v200 offset:35840
	ds_read_b128 v[214:217], v200 offset:36864
	ds_read_b128 v[218:221], v200 offset:37888
	ds_read_b128 v[222:225], v200 offset:38912
	ds_read_b128 v[226:229], v200 offset:39936
	global_load_lds_dwordx4 v[236:237], off
	v_lshl_add_u64 v[236:237], s[66:67], 0, v[166:167]
	s_mov_b32 m0, s83
	s_nop 0
	global_load_lds_dwordx4 v[236:237], off
	s_waitcnt vmcnt(8)
	s_waitcnt lgkmcnt(0)
	s_barrier

	s_waitcnt lgkmcnt(0)
	v_mfma_f32_16x16x32_bf16 v[126:129], v[134:137], v[186:189], v[126:129]
	v_mfma_f32_16x16x32_bf16 v[122:125], v[142:145], v[186:189], v[122:125]
	v_mfma_f32_16x16x32_bf16 v[118:121], v[134:137], v[206:209], v[118:121]
	v_mfma_f32_16x16x32_bf16 v[114:117], v[142:145], v[206:209], v[114:117]
	v_mfma_f32_16x16x32_bf16 v[110:113], v[134:137], v[214:217], v[110:113]
	v_mfma_f32_16x16x32_bf16 v[106:109], v[142:145], v[214:217], v[106:109]
	v_mfma_f32_16x16x32_bf16 v[102:105], v[134:137], v[222:225], v[102:105]
	v_mfma_f32_16x16x32_bf16 v[98:101], v[142:145], v[222:225], v[98:101]
	v_mfma_f32_16x16x32_bf16 v[126:129], v[138:141], v[202:205], v[126:129]
	v_mfma_f32_16x16x32_bf16 v[122:125], v[146:149], v[202:205], v[122:125]
	v_mfma_f32_16x16x32_bf16 v[118:121], v[138:141], v[210:213], v[118:121]
	v_mfma_f32_16x16x32_bf16 v[114:117], v[146:149], v[210:213], v[114:117]
	v_mfma_f32_16x16x32_bf16 v[110:113], v[138:141], v[218:221], v[110:113]
	v_mfma_f32_16x16x32_bf16 v[106:109], v[146:149], v[218:221], v[106:109]
	v_mfma_f32_16x16x32_bf16 v[102:105], v[138:141], v[226:229], v[102:105]
	v_mfma_f32_16x16x32_bf16 v[98:101], v[146:149], v[226:229], v[98:101]


	v_mfma_f32_16x16x32_bf16 v[94:97], v[150:153], v[186:189], v[94:97]
	v_mfma_f32_16x16x32_bf16 v[90:93], v[178:181], v[186:189], v[90:93]
	v_mfma_f32_16x16x32_bf16 v[86:89], v[150:153], v[206:209], v[86:89]
	v_mfma_f32_16x16x32_bf16 v[82:85], v[178:181], v[206:209], v[82:85]
	v_mfma_f32_16x16x32_bf16 v[78:81], v[150:153], v[214:217], v[78:81]
	v_mfma_f32_16x16x32_bf16 v[74:77], v[178:181], v[214:217], v[74:77]
	v_mfma_f32_16x16x32_bf16 v[70:73], v[150:153], v[222:225], v[70:73]
	v_mfma_f32_16x16x32_bf16 v[66:69], v[178:181], v[222:225], v[66:69]
	v_mfma_f32_16x16x32_bf16 v[94:97], v[174:177], v[202:205], v[94:97]
	v_mfma_f32_16x16x32_bf16 v[90:93], v[182:185], v[202:205], v[90:93]
	v_mfma_f32_16x16x32_bf16 v[86:89], v[174:177], v[210:213], v[86:89]
	v_mfma_f32_16x16x32_bf16 v[82:85], v[182:185], v[210:213], v[82:85]
	v_mfma_f32_16x16x32_bf16 v[78:81], v[174:177], v[218:221], v[78:81]
	v_mfma_f32_16x16x32_bf16 v[74:77], v[182:185], v[218:221], v[74:77]
	v_mfma_f32_16x16x32_bf16 v[70:73], v[174:177], v[226:229], v[70:73]
	v_mfma_f32_16x16x32_bf16 v[66:69], v[182:185], v[226:229], v[66:69]

	s_barrier
	s_add_i32 s16, s16, s30
	v_lshl_add_u64 v[190:191], v[190:191], 0, s[34:35]
	s_mov_b32 m0, s16
	ds_read_b128 v[186:189], v200 offset:49152
	ds_read_b128 v[202:205], v200 offset:50176
	ds_read_b128 v[206:209], v200 offset:51200
	ds_read_b128 v[210:213], v200 offset:52224
	ds_read_b128 v[214:217], v200 offset:53248
	ds_read_b128 v[218:221], v200 offset:54272
	ds_read_b128 v[222:225], v200 offset:55296
	ds_read_b128 v[226:229], v200 offset:56320
	global_load_lds_dwordx4 v[190:191], off
	s_add_i32 m0, s16, 0x2000
	s_add_u32 s64, s64, 0x80080
	v_lshl_add_u64 v[190:191], v[230:231], 0, s[34:35]
	s_addc_u32 s65, s65, 0
	s_add_i32 s16, s24, s30
	global_load_lds_dwordx4 v[190:191], off
	v_lshl_add_u64 v[190:191], s[64:65], 0, v[154:155]
	s_mov_b32 m0, s16
	s_nop 0
	global_load_lds_dwordx4 v[190:191], off
	v_lshl_add_u64 v[190:191], s[64:65], 0, v[164:165]
	s_add_i32 m0, s16, 0x2000
	s_nop 0
	global_load_lds_dwordx4 v[190:191], off
	v_lshl_add_u64 v[190:191], v[232:233], 0, s[34:35]
	s_mov_b32 m0, s84
	s_nop 0
	global_load_lds_dwordx4 v[190:191], off
	v_lshl_add_u64 v[190:191], v[234:235], 0, s[34:35]
	s_mov_b32 m0, s85
	s_nop 0
	global_load_lds_dwordx4 v[190:191], off
	s_waitcnt vmcnt(8)
	s_waitcnt lgkmcnt(0)
	s_barrier

	s_waitcnt lgkmcnt(0)
	v_mfma_f32_16x16x32_bf16 v[62:65], v[134:137], v[186:189], v[62:65]
	v_mfma_f32_16x16x32_bf16 v[58:61], v[142:145], v[186:189], v[58:61]
	v_mfma_f32_16x16x32_bf16 v[54:57], v[134:137], v[206:209], v[54:57]
	v_mfma_f32_16x16x32_bf16 v[50:53], v[142:145], v[206:209], v[50:53]
	v_mfma_f32_16x16x32_bf16 v[46:49], v[134:137], v[214:217], v[46:49]
	v_mfma_f32_16x16x32_bf16 v[42:45], v[142:145], v[214:217], v[42:45]
	v_mfma_f32_16x16x32_bf16 v[38:41], v[134:137], v[222:225], v[38:41]
	v_mfma_f32_16x16x32_bf16 v[34:37], v[142:145], v[222:225], v[34:37]
	v_mfma_f32_16x16x32_bf16 v[62:65], v[138:141], v[202:205], v[62:65]
	v_mfma_f32_16x16x32_bf16 v[58:61], v[146:149], v[202:205], v[58:61]
	v_mfma_f32_16x16x32_bf16 v[54:57], v[138:141], v[210:213], v[54:57]
	v_mfma_f32_16x16x32_bf16 v[50:53], v[146:149], v[210:213], v[50:53]
	v_mfma_f32_16x16x32_bf16 v[46:49], v[138:141], v[218:221], v[46:49]
	v_mfma_f32_16x16x32_bf16 v[42:45], v[146:149], v[218:221], v[42:45]
	v_mfma_f32_16x16x32_bf16 v[38:41], v[138:141], v[226:229], v[38:41]
	v_mfma_f32_16x16x32_bf16 v[34:37], v[146:149], v[226:229], v[34:37]


	v_mfma_f32_16x16x32_bf16 v[30:33], v[150:153], v[186:189], v[30:33]
	v_mfma_f32_16x16x32_bf16 v[26:29], v[178:181], v[186:189], v[26:29]
	v_mfma_f32_16x16x32_bf16 v[22:25], v[150:153], v[206:209], v[22:25]
	v_mfma_f32_16x16x32_bf16 v[18:21], v[178:181], v[206:209], v[18:21]
	v_mfma_f32_16x16x32_bf16 v[14:17], v[150:153], v[214:217], v[14:17]
	v_mfma_f32_16x16x32_bf16 v[10:13], v[178:181], v[214:217], v[10:13]
	v_mfma_f32_16x16x32_bf16 v[6:9], v[150:153], v[222:225], v[6:9]
	v_mfma_f32_16x16x32_bf16 v[2:5], v[178:181], v[222:225], v[2:5]
	v_mfma_f32_16x16x32_bf16 v[30:33], v[174:177], v[202:205], v[30:33]
	v_mfma_f32_16x16x32_bf16 v[26:29], v[182:185], v[202:205], v[26:29]
	v_mfma_f32_16x16x32_bf16 v[22:25], v[174:177], v[210:213], v[22:25]
	v_mfma_f32_16x16x32_bf16 v[18:21], v[182:185], v[210:213], v[18:21]
	v_mfma_f32_16x16x32_bf16 v[14:17], v[174:177], v[218:221], v[14:17]
	v_mfma_f32_16x16x32_bf16 v[10:13], v[182:185], v[218:221], v[10:13]
	v_mfma_f32_16x16x32_bf16 v[6:9], v[174:177], v[226:229], v[6:9]
	v_mfma_f32_16x16x32_bf16 v[2:5], v[182:185], v[226:229], v[2:5]

	s_barrier
	s_add_i32 s97, s97, 2
	s_add_u32 s10, s10, 0x100
	s_addc_u32 s11, s11, 0
	s_cmp_gt_u32 s97, 29
	s_cbranch_scc0 .LBB0_473
	s_and_b64 vcc, exec, s[46:47]
	s_cbranch_vccz .LBB0_476
	s_barrier

.LBB0_623:
	s_add_u32 s8, s52, s0
	s_addc_u32 s9, s53, s1
	s_add_u32 s8, s8, 0x100
	s_addc_u32 s9, s9, 0
	s_add_u32 s55, s76, s0
	s_addc_u32 s78, s77, s1
	s_add_i32 s79, 0, 0x10000
	s_cmpk_eq_i32 s0, 0xf00
	s_cselect_b32 s11, s12, s9
	s_cselect_b32 s10, s13, s8
	s_cselect_b32 s9, s26, s78
	s_cselect_b32 s8, s27, s55
	s_add_i32 s55, 0, 0x14000
	v_add_u32_e32 v148, s79, v204
	v_add_u32_e32 v186, s55, v204
	ds_read_b128 v[136:139], v148
	ds_read_b128 v[140:143], v148 offset:1024
	ds_read_b128 v[144:147], v148 offset:2048
	ds_read_b128 v[148:151], v148 offset:3072
	ds_read_b128 v[152:155], v186
	ds_read_b128 v[156:159], v186 offset:1024
	ds_read_b128 v[160:163], v186 offset:2048
	ds_read_b128 v[186:189], v186 offset:3072
	v_lshl_add_u64 v[230:231], v[132:133], 0, s[0:1]
	s_add_i32 m0, s25, 0xc000
	ds_read_b128 v[190:193], v205
	ds_read_b128 v[194:197], v205 offset:1024
	ds_read_b128 v[206:209], v205 offset:2048
	ds_read_b128 v[210:213], v205 offset:3072
	ds_read_b128 v[214:217], v205 offset:4096
	ds_read_b128 v[218:221], v205 offset:5120
	ds_read_b128 v[222:225], v205 offset:6144
	ds_read_b128 v[226:229], v205 offset:7168
	global_load_lds_dwordx4 v[230:231], off
	v_lshl_add_u64 v[230:231], v[134:135], 0, s[0:1]
	s_add_i32 m0, s25, 0xe000
	s_nop 0
	global_load_lds_dwordx4 v[230:231], off
	s_waitcnt vmcnt(8)
	s_waitcnt lgkmcnt(0)
	s_barrier

	s_waitcnt lgkmcnt(0)
	v_mfma_f32_16x16x32_bf16 v[128:131], v[136:139], v[190:193], v[128:131]
	v_mfma_f32_16x16x32_bf16 v[124:127], v[144:147], v[190:193], v[124:127]
	v_mfma_f32_16x16x32_bf16 v[120:123], v[136:139], v[206:209], v[120:123]
	v_mfma_f32_16x16x32_bf16 v[116:119], v[144:147], v[206:209], v[116:119]
	v_mfma_f32_16x16x32_bf16 v[112:115], v[136:139], v[214:217], v[112:115]
	v_mfma_f32_16x16x32_bf16 v[108:111], v[144:147], v[214:217], v[108:111]
	v_mfma_f32_16x16x32_bf16 v[104:107], v[136:139], v[222:225], v[104:107]
	v_mfma_f32_16x16x32_bf16 v[100:103], v[144:147], v[222:225], v[100:103]
	v_mfma_f32_16x16x32_bf16 v[128:131], v[140:143], v[194:197], v[128:131]
	v_mfma_f32_16x16x32_bf16 v[124:127], v[148:151], v[194:197], v[124:127]
	v_mfma_f32_16x16x32_bf16 v[120:123], v[140:143], v[210:213], v[120:123]
	v_mfma_f32_16x16x32_bf16 v[116:119], v[148:151], v[210:213], v[116:119]
	v_mfma_f32_16x16x32_bf16 v[112:115], v[140:143], v[218:221], v[112:115]
	v_mfma_f32_16x16x32_bf16 v[108:111], v[148:151], v[218:221], v[108:111]
	v_mfma_f32_16x16x32_bf16 v[104:107], v[140:143], v[226:229], v[104:107]
	v_mfma_f32_16x16x32_bf16 v[100:103], v[148:151], v[226:229], v[100:103]


	v_mfma_f32_16x16x32_bf16 v[96:99], v[152:155], v[190:193], v[96:99]
	v_mfma_f32_16x16x32_bf16 v[92:95], v[160:163], v[190:193], v[92:95]
	v_mfma_f32_16x16x32_bf16 v[88:91], v[152:155], v[206:209], v[88:91]
	v_mfma_f32_16x16x32_bf16 v[84:87], v[160:163], v[206:209], v[84:87]
	v_mfma_f32_16x16x32_bf16 v[80:83], v[152:155], v[214:217], v[80:83]
	v_mfma_f32_16x16x32_bf16 v[76:79], v[160:163], v[214:217], v[76:79]
	v_mfma_f32_16x16x32_bf16 v[72:75], v[152:155], v[222:225], v[72:75]
	v_mfma_f32_16x16x32_bf16 v[68:71], v[160:163], v[222:225], v[68:71]
	v_mfma_f32_16x16x32_bf16 v[96:99], v[156:159], v[194:197], v[96:99]
	v_mfma_f32_16x16x32_bf16 v[92:95], v[186:189], v[194:197], v[92:95]
	v_mfma_f32_16x16x32_bf16 v[88:91], v[156:159], v[210:213], v[88:91]
	v_mfma_f32_16x16x32_bf16 v[84:87], v[186:189], v[210:213], v[84:87]
	v_mfma_f32_16x16x32_bf16 v[80:83], v[156:159], v[218:221], v[80:83]
	v_mfma_f32_16x16x32_bf16 v[76:79], v[186:189], v[218:221], v[76:79]
	v_mfma_f32_16x16x32_bf16 v[72:75], v[156:159], v[226:229], v[72:75]
	v_mfma_f32_16x16x32_bf16 v[68:71], v[186:189], v[226:229], v[68:71]

	s_barrier
	s_add_i32 s78, s79, s24
	v_lshl_add_u64 v[230:231], s[8:9], 0, v[170:171]
	s_mov_b32 m0, s78
	ds_read_b128 v[190:193], v205 offset:16384
	ds_read_b128 v[194:197], v205 offset:17408
	ds_read_b128 v[206:209], v205 offset:18432
	ds_read_b128 v[210:213], v205 offset:19456
	ds_read_b128 v[214:217], v205 offset:20480
	ds_read_b128 v[218:221], v205 offset:21504
	ds_read_b128 v[222:225], v205 offset:22528
	ds_read_b128 v[226:229], v205 offset:23552
	global_load_lds_dwordx4 v[230:231], off
	s_add_i32 m0, s78, 0x2000
	s_add_u32 s78, s8, 0x80000
	v_lshl_add_u64 v[232:233], s[8:9], 0, v[174:175]
	s_addc_u32 s79, s9, 0
	s_add_i32 s55, s55, s24
	global_load_lds_dwordx4 v[232:233], off
	v_lshl_add_u64 v[234:235], s[78:79], 0, v[170:171]
	s_mov_b32 m0, s55
	v_lshl_add_u64 v[236:237], s[10:11], 0, v[172:173]
	global_load_lds_dwordx4 v[234:235], off
	v_lshl_add_u64 v[234:235], s[78:79], 0, v[174:175]
	s_add_i32 m0, s55, 0x2000
	s_nop 0
	global_load_lds_dwordx4 v[234:235], off
	v_lshl_add_u64 v[234:235], s[10:11], 0, v[168:169]
	s_mov_b32 m0, s25
	s_nop 0
	global_load_lds_dwordx4 v[234:235], off
	s_mov_b32 m0, s30
	s_nop 0
	global_load_lds_dwordx4 v[236:237], off
	s_waitcnt vmcnt(8)
	s_waitcnt lgkmcnt(0)
	s_barrier

	s_waitcnt lgkmcnt(0)
	v_mfma_f32_16x16x32_bf16 v[64:67], v[136:139], v[190:193], v[64:67]
	v_mfma_f32_16x16x32_bf16 v[60:63], v[144:147], v[190:193], v[60:63]
	v_mfma_f32_16x16x32_bf16 v[56:59], v[136:139], v[206:209], v[56:59]
	v_mfma_f32_16x16x32_bf16 v[52:55], v[144:147], v[206:209], v[52:55]
	v_mfma_f32_16x16x32_bf16 v[48:51], v[136:139], v[214:217], v[48:51]
	v_mfma_f32_16x16x32_bf16 v[44:47], v[144:147], v[214:217], v[44:47]
	v_mfma_f32_16x16x32_bf16 v[40:43], v[136:139], v[222:225], v[40:43]
	v_mfma_f32_16x16x32_bf16 v[36:39], v[144:147], v[222:225], v[36:39]
	v_mfma_f32_16x16x32_bf16 v[64:67], v[140:143], v[194:197], v[64:67]
	v_mfma_f32_16x16x32_bf16 v[60:63], v[148:151], v[194:197], v[60:63]
	v_mfma_f32_16x16x32_bf16 v[56:59], v[140:143], v[210:213], v[56:59]
	v_mfma_f32_16x16x32_bf16 v[52:55], v[148:151], v[210:213], v[52:55]
	v_mfma_f32_16x16x32_bf16 v[48:51], v[140:143], v[218:221], v[48:51]
	v_mfma_f32_16x16x32_bf16 v[44:47], v[148:151], v[218:221], v[44:47]
	v_mfma_f32_16x16x32_bf16 v[40:43], v[140:143], v[226:229], v[40:43]
	v_mfma_f32_16x16x32_bf16 v[36:39], v[148:151], v[226:229], v[36:39]


	v_mfma_f32_16x16x32_bf16 v[32:35], v[152:155], v[190:193], v[32:35]
	v_mfma_f32_16x16x32_bf16 v[28:31], v[160:163], v[190:193], v[28:31]
	v_mfma_f32_16x16x32_bf16 v[24:27], v[152:155], v[206:209], v[24:27]
	v_mfma_f32_16x16x32_bf16 v[20:23], v[160:163], v[206:209], v[20:23]
	v_mfma_f32_16x16x32_bf16 v[16:19], v[152:155], v[214:217], v[16:19]
	v_mfma_f32_16x16x32_bf16 v[12:15], v[160:163], v[214:217], v[12:15]
	v_mfma_f32_16x16x32_bf16 v[8:11], v[152:155], v[222:225], v[8:11]
	v_mfma_f32_16x16x32_bf16 v[4:7], v[160:163], v[222:225], v[4:7]
	v_mfma_f32_16x16x32_bf16 v[32:35], v[156:159], v[194:197], v[32:35]
	v_mfma_f32_16x16x32_bf16 v[28:31], v[186:189], v[194:197], v[28:31]
	v_mfma_f32_16x16x32_bf16 v[24:27], v[156:159], v[210:213], v[24:27]
	v_mfma_f32_16x16x32_bf16 v[20:23], v[186:189], v[210:213], v[20:23]
	v_mfma_f32_16x16x32_bf16 v[16:19], v[156:159], v[218:221], v[16:19]
	v_mfma_f32_16x16x32_bf16 v[12:15], v[186:189], v[218:221], v[12:15]
	v_mfma_f32_16x16x32_bf16 v[8:11], v[156:159], v[226:229], v[8:11]
	v_mfma_f32_16x16x32_bf16 v[4:7], v[186:189], v[226:229], v[4:7]

	s_barrier
	s_add_i32 s55, 0, 0x18000
	s_add_i32 s78, 0, 0x1c000
	v_add_u32_e32 v148, s55, v204
	v_add_u32_e32 v186, s78, v204
	ds_read_b128 v[136:139], v148
	ds_read_b128 v[140:143], v148 offset:1024
	ds_read_b128 v[144:147], v148 offset:2048
	ds_read_b128 v[148:151], v148 offset:3072
	ds_read_b128 v[152:155], v186
	ds_read_b128 v[156:159], v186 offset:1024
	ds_read_b128 v[160:163], v186 offset:2048
	ds_read_b128 v[186:189], v186 offset:3072
	s_add_u32 s10, s10, 0x80000
	s_addc_u32 s11, s11, 0
	s_mov_b32 m0, s31
	v_lshl_add_u64 v[238:239], s[10:11], 0, v[168:169]
	ds_read_b128 v[190:193], v205 offset:32768
	ds_read_b128 v[194:197], v205 offset:33792
	ds_read_b128 v[206:209], v205 offset:34816
	ds_read_b128 v[210:213], v205 offset:35840
	ds_read_b128 v[214:217], v205 offset:36864
	ds_read_b128 v[218:221], v205 offset:37888
	ds_read_b128 v[222:225], v205 offset:38912
	ds_read_b128 v[226:229], v205 offset:39936
	global_load_lds_dwordx4 v[238:239], off
	v_lshl_add_u64 v[238:239], s[10:11], 0, v[172:173]
	s_mov_b32 m0, s36
	s_nop 0
	global_load_lds_dwordx4 v[238:239], off
	s_waitcnt vmcnt(8)
	s_waitcnt lgkmcnt(0)
	s_barrier

	s_waitcnt lgkmcnt(0)
	v_mfma_f32_16x16x32_bf16 v[128:131], v[136:139], v[190:193], v[128:131]
	v_mfma_f32_16x16x32_bf16 v[124:127], v[144:147], v[190:193], v[124:127]
	v_mfma_f32_16x16x32_bf16 v[120:123], v[136:139], v[206:209], v[120:123]
	v_mfma_f32_16x16x32_bf16 v[116:119], v[144:147], v[206:209], v[116:119]
	v_mfma_f32_16x16x32_bf16 v[112:115], v[136:139], v[214:217], v[112:115]
	v_mfma_f32_16x16x32_bf16 v[108:111], v[144:147], v[214:217], v[108:111]
	v_mfma_f32_16x16x32_bf16 v[104:107], v[136:139], v[222:225], v[104:107]
	v_mfma_f32_16x16x32_bf16 v[100:103], v[144:147], v[222:225], v[100:103]
	v_mfma_f32_16x16x32_bf16 v[128:131], v[140:143], v[194:197], v[128:131]
	v_mfma_f32_16x16x32_bf16 v[124:127], v[148:151], v[194:197], v[124:127]
	v_mfma_f32_16x16x32_bf16 v[120:123], v[140:143], v[210:213], v[120:123]
	v_mfma_f32_16x16x32_bf16 v[116:119], v[148:151], v[210:213], v[116:119]
	v_mfma_f32_16x16x32_bf16 v[112:115], v[140:143], v[218:221], v[112:115]
	v_mfma_f32_16x16x32_bf16 v[108:111], v[148:151], v[218:221], v[108:111]
	v_mfma_f32_16x16x32_bf16 v[104:107], v[140:143], v[226:229], v[104:107]
	v_mfma_f32_16x16x32_bf16 v[100:103], v[148:151], v[226:229], v[100:103]


	v_mfma_f32_16x16x32_bf16 v[96:99], v[152:155], v[190:193], v[96:99]
	v_mfma_f32_16x16x32_bf16 v[92:95], v[160:163], v[190:193], v[92:95]
	v_mfma_f32_16x16x32_bf16 v[88:91], v[152:155], v[206:209], v[88:91]
	v_mfma_f32_16x16x32_bf16 v[84:87], v[160:163], v[206:209], v[84:87]
	v_mfma_f32_16x16x32_bf16 v[80:83], v[152:155], v[214:217], v[80:83]
	v_mfma_f32_16x16x32_bf16 v[76:79], v[160:163], v[214:217], v[76:79]
	v_mfma_f32_16x16x32_bf16 v[72:75], v[152:155], v[222:225], v[72:75]
	v_mfma_f32_16x16x32_bf16 v[68:71], v[160:163], v[222:225], v[68:71]
	v_mfma_f32_16x16x32_bf16 v[96:99], v[156:159], v[194:197], v[96:99]
	v_mfma_f32_16x16x32_bf16 v[92:95], v[186:189], v[194:197], v[92:95]
	v_mfma_f32_16x16x32_bf16 v[88:91], v[156:159], v[210:213], v[88:91]
	v_mfma_f32_16x16x32_bf16 v[84:87], v[186:189], v[210:213], v[84:87]
	v_mfma_f32_16x16x32_bf16 v[80:83], v[156:159], v[218:221], v[80:83]
	v_mfma_f32_16x16x32_bf16 v[76:79], v[186:189], v[218:221], v[76:79]
	v_mfma_f32_16x16x32_bf16 v[72:75], v[156:159], v[226:229], v[72:75]
	v_mfma_f32_16x16x32_bf16 v[68:71], v[186:189], v[226:229], v[68:71]

	s_barrier
	s_add_i32 s10, s55, s24
	v_lshl_add_u64 v[230:231], v[230:231], 0, s[28:29]
	s_mov_b32 m0, s10
	ds_read_b128 v[190:193], v205 offset:49152
	ds_read_b128 v[194:197], v205 offset:50176
	ds_read_b128 v[206:209], v205 offset:51200
	ds_read_b128 v[210:213], v205 offset:52224
	ds_read_b128 v[214:217], v205 offset:53248
	ds_read_b128 v[218:221], v205 offset:54272
	ds_read_b128 v[222:225], v205 offset:55296
	ds_read_b128 v[226:229], v205 offset:56320
	global_load_lds_dwordx4 v[230:231], off
	s_add_i32 m0, s10, 0x2000
	s_add_u32 s8, s8, 0x80080
	v_lshl_add_u64 v[230:231], v[232:233], 0, s[28:29]
	s_addc_u32 s9, s9, 0
	s_add_i32 s10, s78, s24
	global_load_lds_dwordx4 v[230:231], off
	v_lshl_add_u64 v[230:231], s[8:9], 0, v[170:171]
	s_mov_b32 m0, s10
	s_nop 0
	global_load_lds_dwordx4 v[230:231], off
	v_lshl_add_u64 v[230:231], s[8:9], 0, v[174:175]
	s_add_i32 m0, s10, 0x2000
	s_nop 0
	global_load_lds_dwordx4 v[230:231], off
	v_lshl_add_u64 v[230:231], v[234:235], 0, s[28:29]
	s_mov_b32 m0, s45
	s_nop 0
	global_load_lds_dwordx4 v[230:231], off
	v_lshl_add_u64 v[230:231], v[236:237], 0, s[28:29]
	s_mov_b32 m0, s60
	s_nop 0
	global_load_lds_dwordx4 v[230:231], off
	s_waitcnt vmcnt(8)
	s_waitcnt lgkmcnt(0)
	s_barrier

	s_waitcnt lgkmcnt(0)
	v_mfma_f32_16x16x32_bf16 v[64:67], v[136:139], v[190:193], v[64:67]
	v_mfma_f32_16x16x32_bf16 v[60:63], v[144:147], v[190:193], v[60:63]
	v_mfma_f32_16x16x32_bf16 v[56:59], v[136:139], v[206:209], v[56:59]
	v_mfma_f32_16x16x32_bf16 v[52:55], v[144:147], v[206:209], v[52:55]
	v_mfma_f32_16x16x32_bf16 v[48:51], v[136:139], v[214:217], v[48:51]
	v_mfma_f32_16x16x32_bf16 v[44:47], v[144:147], v[214:217], v[44:47]
	v_mfma_f32_16x16x32_bf16 v[40:43], v[136:139], v[222:225], v[40:43]
	v_mfma_f32_16x16x32_bf16 v[36:39], v[144:147], v[222:225], v[36:39]
	v_mfma_f32_16x16x32_bf16 v[64:67], v[140:143], v[194:197], v[64:67]
	v_mfma_f32_16x16x32_bf16 v[60:63], v[148:151], v[194:197], v[60:63]
	v_mfma_f32_16x16x32_bf16 v[56:59], v[140:143], v[210:213], v[56:59]
	v_mfma_f32_16x16x32_bf16 v[52:55], v[148:151], v[210:213], v[52:55]
	v_mfma_f32_16x16x32_bf16 v[48:51], v[140:143], v[218:221], v[48:51]
	v_mfma_f32_16x16x32_bf16 v[44:47], v[148:151], v[218:221], v[44:47]
	v_mfma_f32_16x16x32_bf16 v[40:43], v[140:143], v[226:229], v[40:43]
	v_mfma_f32_16x16x32_bf16 v[36:39], v[148:151], v[226:229], v[36:39]


	v_mfma_f32_16x16x32_bf16 v[32:35], v[152:155], v[190:193], v[32:35]
	v_mfma_f32_16x16x32_bf16 v[28:31], v[160:163], v[190:193], v[28:31]
	v_mfma_f32_16x16x32_bf16 v[24:27], v[152:155], v[206:209], v[24:27]
	v_mfma_f32_16x16x32_bf16 v[20:23], v[160:163], v[206:209], v[20:23]
	v_mfma_f32_16x16x32_bf16 v[16:19], v[152:155], v[214:217], v[16:19]
	v_mfma_f32_16x16x32_bf16 v[12:15], v[160:163], v[214:217], v[12:15]
	v_mfma_f32_16x16x32_bf16 v[8:11], v[152:155], v[222:225], v[8:11]
	v_mfma_f32_16x16x32_bf16 v[4:7], v[160:163], v[222:225], v[4:7]
	v_mfma_f32_16x16x32_bf16 v[32:35], v[156:159], v[194:197], v[32:35]
	v_mfma_f32_16x16x32_bf16 v[28:31], v[186:189], v[194:197], v[28:31]
	v_mfma_f32_16x16x32_bf16 v[24:27], v[156:159], v[210:213], v[24:27]
	v_mfma_f32_16x16x32_bf16 v[20:23], v[186:189], v[210:213], v[20:23]
	v_mfma_f32_16x16x32_bf16 v[16:19], v[156:159], v[218:221], v[16:19]
	v_mfma_f32_16x16x32_bf16 v[12:15], v[186:189], v[218:221], v[12:15]
	v_mfma_f32_16x16x32_bf16 v[8:11], v[156:159], v[226:229], v[8:11]
	v_mfma_f32_16x16x32_bf16 v[4:7], v[186:189], v[226:229], v[4:7]

	s_barrier
	s_add_i32 s43, s43, 2
	s_add_u32 s0, s0, 0x100
	s_addc_u32 s1, s1, 0
	s_cmp_gt_u32 s43, 29
	s_cbranch_scc0 .LBB0_623
	s_and_b64 vcc, exec, s[50:51]
	s_cbranch_vccz .LBB0_626
	s_barrier

.LBB0_866:
	s_add_u32 s24, s34, s10
	s_addc_u32 s25, s35, s11
	s_add_u32 s24, s24, 0x100
	s_addc_u32 s25, s25, 0
	s_add_u32 s67, s60, s10
	s_addc_u32 s74, s61, s11
	s_add_i32 s75, 0, 0x10000
	s_cmpk_eq_i32 s10, 0xf00
	s_cselect_b32 s31, s27, s25
	s_cselect_b32 s30, s62, s24
	s_cselect_b32 s25, s15, s74
	s_cselect_b32 s24, s63, s67
	s_add_i32 s67, 0, 0x14000
	v_add_u32_e32 v148, s75, v189
	v_add_u32_e32 v178, s67, v189
	ds_read_b128 v[136:139], v148
	ds_read_b128 v[140:143], v148 offset:1024
	ds_read_b128 v[144:147], v148 offset:2048
	ds_read_b128 v[148:151], v148 offset:3072
	ds_read_b128 v[152:155], v178
	ds_read_b128 v[170:173], v178 offset:1024
	ds_read_b128 v[174:177], v178 offset:2048
	ds_read_b128 v[178:181], v178 offset:3072
	v_lshl_add_u64 v[186:187], v[132:133], 0, s[10:11]
	s_add_i32 m0, s48, 0xc000
	ds_read_b128 v[182:185], v191
	ds_read_b128 v[192:195], v191 offset:1024
	ds_read_b128 v[204:207], v191 offset:2048
	ds_read_b128 v[208:211], v191 offset:3072
	ds_read_b128 v[212:215], v191 offset:4096
	ds_read_b128 v[216:219], v191 offset:5120
	ds_read_b128 v[220:223], v191 offset:6144
	ds_read_b128 v[224:227], v191 offset:7168
	global_load_lds_dwordx4 v[186:187], off
	v_lshl_add_u64 v[186:187], v[134:135], 0, s[10:11]
	s_add_i32 m0, s48, 0xe000
	s_nop 0
	global_load_lds_dwordx4 v[186:187], off
	s_waitcnt vmcnt(8)
	s_waitcnt lgkmcnt(0)
	s_barrier

	s_waitcnt lgkmcnt(0)
	v_mfma_f32_16x16x32_bf16 v[128:131], v[136:139], v[182:185], v[128:131]
	v_mfma_f32_16x16x32_bf16 v[124:127], v[144:147], v[182:185], v[124:127]
	v_mfma_f32_16x16x32_bf16 v[120:123], v[136:139], v[204:207], v[120:123]
	v_mfma_f32_16x16x32_bf16 v[116:119], v[144:147], v[204:207], v[116:119]
	v_mfma_f32_16x16x32_bf16 v[112:115], v[136:139], v[212:215], v[112:115]
	v_mfma_f32_16x16x32_bf16 v[108:111], v[144:147], v[212:215], v[108:111]
	v_mfma_f32_16x16x32_bf16 v[104:107], v[136:139], v[220:223], v[104:107]
	v_mfma_f32_16x16x32_bf16 v[100:103], v[144:147], v[220:223], v[100:103]
	v_mfma_f32_16x16x32_bf16 v[128:131], v[140:143], v[192:195], v[128:131]
	v_mfma_f32_16x16x32_bf16 v[124:127], v[148:151], v[192:195], v[124:127]
	v_mfma_f32_16x16x32_bf16 v[120:123], v[140:143], v[208:211], v[120:123]
	v_mfma_f32_16x16x32_bf16 v[116:119], v[148:151], v[208:211], v[116:119]
	v_mfma_f32_16x16x32_bf16 v[112:115], v[140:143], v[216:219], v[112:115]
	v_mfma_f32_16x16x32_bf16 v[108:111], v[148:151], v[216:219], v[108:111]
	v_mfma_f32_16x16x32_bf16 v[104:107], v[140:143], v[224:227], v[104:107]
	v_mfma_f32_16x16x32_bf16 v[100:103], v[148:151], v[224:227], v[100:103]


	v_mfma_f32_16x16x32_bf16 v[96:99], v[152:155], v[182:185], v[96:99]
	v_mfma_f32_16x16x32_bf16 v[92:95], v[174:177], v[182:185], v[92:95]
	v_mfma_f32_16x16x32_bf16 v[88:91], v[152:155], v[204:207], v[88:91]
	v_mfma_f32_16x16x32_bf16 v[84:87], v[174:177], v[204:207], v[84:87]
	v_mfma_f32_16x16x32_bf16 v[80:83], v[152:155], v[212:215], v[80:83]
	v_mfma_f32_16x16x32_bf16 v[76:79], v[174:177], v[212:215], v[76:79]
	v_mfma_f32_16x16x32_bf16 v[72:75], v[152:155], v[220:223], v[72:75]
	v_mfma_f32_16x16x32_bf16 v[68:71], v[174:177], v[220:223], v[68:71]
	v_mfma_f32_16x16x32_bf16 v[96:99], v[170:173], v[192:195], v[96:99]
	v_mfma_f32_16x16x32_bf16 v[92:95], v[178:181], v[192:195], v[92:95]
	v_mfma_f32_16x16x32_bf16 v[88:91], v[170:173], v[208:211], v[88:91]
	v_mfma_f32_16x16x32_bf16 v[84:87], v[178:181], v[208:211], v[84:87]
	v_mfma_f32_16x16x32_bf16 v[80:83], v[170:173], v[216:219], v[80:83]
	v_mfma_f32_16x16x32_bf16 v[76:79], v[178:181], v[216:219], v[76:79]
	v_mfma_f32_16x16x32_bf16 v[72:75], v[170:173], v[224:227], v[72:75]
	v_mfma_f32_16x16x32_bf16 v[68:71], v[178:181], v[224:227], v[68:71]

	s_barrier
	s_add_i32 s74, s75, s47
	v_lshl_add_u64 v[186:187], s[24:25], 0, v[2:3]
	s_mov_b32 m0, s74
	ds_read_b128 v[182:185], v191 offset:16384
	ds_read_b128 v[192:195], v191 offset:17408
	ds_read_b128 v[204:207], v191 offset:18432
	ds_read_b128 v[208:211], v191 offset:19456
	ds_read_b128 v[212:215], v191 offset:20480
	ds_read_b128 v[216:219], v191 offset:21504
	ds_read_b128 v[220:223], v191 offset:22528
	ds_read_b128 v[224:227], v191 offset:23552
	global_load_lds_dwordx4 v[186:187], off
	s_add_i32 m0, s74, 0x2000
	s_add_u32 s74, s24, 0x80000
	v_lshl_add_u64 v[196:197], s[24:25], 0, v[156:157]
	s_addc_u32 s75, s25, 0
	s_add_i32 s67, s67, s47
	global_load_lds_dwordx4 v[196:197], off
	v_lshl_add_u64 v[228:229], s[74:75], 0, v[2:3]
	s_mov_b32 m0, s67
	v_lshl_add_u64 v[230:231], s[30:31], 0, v[158:159]
	global_load_lds_dwordx4 v[228:229], off
	v_lshl_add_u64 v[228:229], s[74:75], 0, v[156:157]
	s_add_i32 m0, s67, 0x2000
	s_nop 0
	global_load_lds_dwordx4 v[228:229], off
	v_lshl_add_u64 v[228:229], s[30:31], 0, v[160:161]
	s_mov_b32 m0, s48
	s_nop 0
	global_load_lds_dwordx4 v[228:229], off
	s_mov_b32 m0, s49
	s_nop 0
	global_load_lds_dwordx4 v[230:231], off
	s_waitcnt vmcnt(8)
	s_waitcnt lgkmcnt(0)
	s_barrier

	s_waitcnt lgkmcnt(0)
	v_mfma_f32_16x16x32_bf16 v[64:67], v[136:139], v[182:185], v[64:67]
	v_mfma_f32_16x16x32_bf16 v[60:63], v[144:147], v[182:185], v[60:63]
	v_mfma_f32_16x16x32_bf16 v[56:59], v[136:139], v[204:207], v[56:59]
	v_mfma_f32_16x16x32_bf16 v[52:55], v[144:147], v[204:207], v[52:55]
	v_mfma_f32_16x16x32_bf16 v[48:51], v[136:139], v[212:215], v[48:51]
	v_mfma_f32_16x16x32_bf16 v[44:47], v[144:147], v[212:215], v[44:47]
	v_mfma_f32_16x16x32_bf16 v[40:43], v[136:139], v[220:223], v[40:43]
	v_mfma_f32_16x16x32_bf16 v[36:39], v[144:147], v[220:223], v[36:39]
	v_mfma_f32_16x16x32_bf16 v[64:67], v[140:143], v[192:195], v[64:67]
	v_mfma_f32_16x16x32_bf16 v[60:63], v[148:151], v[192:195], v[60:63]
	v_mfma_f32_16x16x32_bf16 v[56:59], v[140:143], v[208:211], v[56:59]
	v_mfma_f32_16x16x32_bf16 v[52:55], v[148:151], v[208:211], v[52:55]
	v_mfma_f32_16x16x32_bf16 v[48:51], v[140:143], v[216:219], v[48:51]
	v_mfma_f32_16x16x32_bf16 v[44:47], v[148:151], v[216:219], v[44:47]
	v_mfma_f32_16x16x32_bf16 v[40:43], v[140:143], v[224:227], v[40:43]
	v_mfma_f32_16x16x32_bf16 v[36:39], v[148:151], v[224:227], v[36:39]


	v_mfma_f32_16x16x32_bf16 v[32:35], v[152:155], v[182:185], v[32:35]
	v_mfma_f32_16x16x32_bf16 v[28:31], v[174:177], v[182:185], v[28:31]
	v_mfma_f32_16x16x32_bf16 v[24:27], v[152:155], v[204:207], v[24:27]
	v_mfma_f32_16x16x32_bf16 v[20:23], v[174:177], v[204:207], v[20:23]
	v_mfma_f32_16x16x32_bf16 v[16:19], v[152:155], v[212:215], v[16:19]
	v_mfma_f32_16x16x32_bf16 v[12:15], v[174:177], v[212:215], v[12:15]
	v_mfma_f32_16x16x32_bf16 v[8:11], v[152:155], v[220:223], v[8:11]
	v_mfma_f32_16x16x32_bf16 v[4:7], v[174:177], v[220:223], v[4:7]
	v_mfma_f32_16x16x32_bf16 v[32:35], v[170:173], v[192:195], v[32:35]
	v_mfma_f32_16x16x32_bf16 v[28:31], v[178:181], v[192:195], v[28:31]
	v_mfma_f32_16x16x32_bf16 v[24:27], v[170:173], v[208:211], v[24:27]
	v_mfma_f32_16x16x32_bf16 v[20:23], v[178:181], v[208:211], v[20:23]
	v_mfma_f32_16x16x32_bf16 v[16:19], v[170:173], v[216:219], v[16:19]
	v_mfma_f32_16x16x32_bf16 v[12:15], v[178:181], v[216:219], v[12:15]
	v_mfma_f32_16x16x32_bf16 v[8:11], v[170:173], v[224:227], v[8:11]
	v_mfma_f32_16x16x32_bf16 v[4:7], v[178:181], v[224:227], v[4:7]

	s_barrier
	s_add_i32 s67, 0, 0x18000
	s_add_i32 s74, 0, 0x1c000
	v_add_u32_e32 v148, s67, v189
	v_add_u32_e32 v178, s74, v189
	ds_read_b128 v[136:139], v148
	ds_read_b128 v[140:143], v148 offset:1024
	ds_read_b128 v[144:147], v148 offset:2048
	ds_read_b128 v[148:151], v148 offset:3072
	ds_read_b128 v[152:155], v178
	ds_read_b128 v[170:173], v178 offset:1024
	ds_read_b128 v[174:177], v178 offset:2048
	ds_read_b128 v[178:181], v178 offset:3072
	s_add_u32 s30, s30, 0x80000
	s_addc_u32 s31, s31, 0
	s_mov_b32 m0, s50
	v_lshl_add_u64 v[232:233], s[30:31], 0, v[160:161]
	ds_read_b128 v[182:185], v191 offset:32768
	ds_read_b128 v[192:195], v191 offset:33792
	ds_read_b128 v[204:207], v191 offset:34816
	ds_read_b128 v[208:211], v191 offset:35840
	ds_read_b128 v[212:215], v191 offset:36864
	ds_read_b128 v[216:219], v191 offset:37888
	ds_read_b128 v[220:223], v191 offset:38912
	ds_read_b128 v[224:227], v191 offset:39936
	global_load_lds_dwordx4 v[232:233], off
	v_lshl_add_u64 v[232:233], s[30:31], 0, v[158:159]
	s_mov_b32 m0, s51
	s_nop 0
	global_load_lds_dwordx4 v[232:233], off
	s_waitcnt vmcnt(8)
	s_waitcnt lgkmcnt(0)
	s_barrier

	s_waitcnt lgkmcnt(0)
	v_mfma_f32_16x16x32_bf16 v[128:131], v[136:139], v[182:185], v[128:131]
	v_mfma_f32_16x16x32_bf16 v[124:127], v[144:147], v[182:185], v[124:127]
	v_mfma_f32_16x16x32_bf16 v[120:123], v[136:139], v[204:207], v[120:123]
	v_mfma_f32_16x16x32_bf16 v[116:119], v[144:147], v[204:207], v[116:119]
	v_mfma_f32_16x16x32_bf16 v[112:115], v[136:139], v[212:215], v[112:115]
	v_mfma_f32_16x16x32_bf16 v[108:111], v[144:147], v[212:215], v[108:111]
	v_mfma_f32_16x16x32_bf16 v[104:107], v[136:139], v[220:223], v[104:107]
	v_mfma_f32_16x16x32_bf16 v[100:103], v[144:147], v[220:223], v[100:103]
	v_mfma_f32_16x16x32_bf16 v[128:131], v[140:143], v[192:195], v[128:131]
	v_mfma_f32_16x16x32_bf16 v[124:127], v[148:151], v[192:195], v[124:127]
	v_mfma_f32_16x16x32_bf16 v[120:123], v[140:143], v[208:211], v[120:123]
	v_mfma_f32_16x16x32_bf16 v[116:119], v[148:151], v[208:211], v[116:119]
	v_mfma_f32_16x16x32_bf16 v[112:115], v[140:143], v[216:219], v[112:115]
	v_mfma_f32_16x16x32_bf16 v[108:111], v[148:151], v[216:219], v[108:111]
	v_mfma_f32_16x16x32_bf16 v[104:107], v[140:143], v[224:227], v[104:107]
	v_mfma_f32_16x16x32_bf16 v[100:103], v[148:151], v[224:227], v[100:103]


	v_mfma_f32_16x16x32_bf16 v[96:99], v[152:155], v[182:185], v[96:99]
	v_mfma_f32_16x16x32_bf16 v[92:95], v[174:177], v[182:185], v[92:95]
	v_mfma_f32_16x16x32_bf16 v[88:91], v[152:155], v[204:207], v[88:91]
	v_mfma_f32_16x16x32_bf16 v[84:87], v[174:177], v[204:207], v[84:87]
	v_mfma_f32_16x16x32_bf16 v[80:83], v[152:155], v[212:215], v[80:83]
	v_mfma_f32_16x16x32_bf16 v[76:79], v[174:177], v[212:215], v[76:79]
	v_mfma_f32_16x16x32_bf16 v[72:75], v[152:155], v[220:223], v[72:75]
	v_mfma_f32_16x16x32_bf16 v[68:71], v[174:177], v[220:223], v[68:71]
	v_mfma_f32_16x16x32_bf16 v[96:99], v[170:173], v[192:195], v[96:99]
	v_mfma_f32_16x16x32_bf16 v[92:95], v[178:181], v[192:195], v[92:95]
	v_mfma_f32_16x16x32_bf16 v[88:91], v[170:173], v[208:211], v[88:91]
	v_mfma_f32_16x16x32_bf16 v[84:87], v[178:181], v[208:211], v[84:87]
	v_mfma_f32_16x16x32_bf16 v[80:83], v[170:173], v[216:219], v[80:83]
	v_mfma_f32_16x16x32_bf16 v[76:79], v[178:181], v[216:219], v[76:79]
	v_mfma_f32_16x16x32_bf16 v[72:75], v[170:173], v[224:227], v[72:75]
	v_mfma_f32_16x16x32_bf16 v[68:71], v[178:181], v[224:227], v[68:71]

	s_barrier
	s_add_i32 s30, s67, s47
	v_lshl_add_u64 v[186:187], v[186:187], 0, s[28:29]
	s_mov_b32 m0, s30
	ds_read_b128 v[182:185], v191 offset:49152
	ds_read_b128 v[192:195], v191 offset:50176
	ds_read_b128 v[204:207], v191 offset:51200
	ds_read_b128 v[208:211], v191 offset:52224
	ds_read_b128 v[212:215], v191 offset:53248
	ds_read_b128 v[216:219], v191 offset:54272
	ds_read_b128 v[220:223], v191 offset:55296
	ds_read_b128 v[224:227], v191 offset:56320
	global_load_lds_dwordx4 v[186:187], off
	s_add_i32 m0, s30, 0x2000
	s_add_u32 s24, s24, 0x80080
	v_lshl_add_u64 v[186:187], v[196:197], 0, s[28:29]
	s_addc_u32 s25, s25, 0
	s_add_i32 s30, s74, s47
	global_load_lds_dwordx4 v[186:187], off
	v_lshl_add_u64 v[186:187], s[24:25], 0, v[2:3]
	s_mov_b32 m0, s30
	s_nop 0
	global_load_lds_dwordx4 v[186:187], off
	v_lshl_add_u64 v[186:187], s[24:25], 0, v[156:157]
	s_add_i32 m0, s30, 0x2000
	s_nop 0
	global_load_lds_dwordx4 v[186:187], off
	v_lshl_add_u64 v[186:187], v[228:229], 0, s[28:29]
	s_mov_b32 m0, s52
	s_nop 0
	global_load_lds_dwordx4 v[186:187], off
	v_lshl_add_u64 v[186:187], v[230:231], 0, s[28:29]
	s_mov_b32 m0, s53
	s_nop 0
	global_load_lds_dwordx4 v[186:187], off
	s_waitcnt vmcnt(8)
	s_waitcnt lgkmcnt(0)
	s_barrier

	s_waitcnt lgkmcnt(0)
	v_mfma_f32_16x16x32_bf16 v[64:67], v[136:139], v[182:185], v[64:67]
	v_mfma_f32_16x16x32_bf16 v[60:63], v[144:147], v[182:185], v[60:63]
	v_mfma_f32_16x16x32_bf16 v[56:59], v[136:139], v[204:207], v[56:59]
	v_mfma_f32_16x16x32_bf16 v[52:55], v[144:147], v[204:207], v[52:55]
	v_mfma_f32_16x16x32_bf16 v[48:51], v[136:139], v[212:215], v[48:51]
	v_mfma_f32_16x16x32_bf16 v[44:47], v[144:147], v[212:215], v[44:47]
	v_mfma_f32_16x16x32_bf16 v[40:43], v[136:139], v[220:223], v[40:43]
	v_mfma_f32_16x16x32_bf16 v[36:39], v[144:147], v[220:223], v[36:39]
	v_mfma_f32_16x16x32_bf16 v[64:67], v[140:143], v[192:195], v[64:67]
	v_mfma_f32_16x16x32_bf16 v[60:63], v[148:151], v[192:195], v[60:63]
	v_mfma_f32_16x16x32_bf16 v[56:59], v[140:143], v[208:211], v[56:59]
	v_mfma_f32_16x16x32_bf16 v[52:55], v[148:151], v[208:211], v[52:55]
	v_mfma_f32_16x16x32_bf16 v[48:51], v[140:143], v[216:219], v[48:51]
	v_mfma_f32_16x16x32_bf16 v[44:47], v[148:151], v[216:219], v[44:47]
	v_mfma_f32_16x16x32_bf16 v[40:43], v[140:143], v[224:227], v[40:43]
	v_mfma_f32_16x16x32_bf16 v[36:39], v[148:151], v[224:227], v[36:39]


	v_mfma_f32_16x16x32_bf16 v[32:35], v[152:155], v[182:185], v[32:35]
	v_mfma_f32_16x16x32_bf16 v[28:31], v[174:177], v[182:185], v[28:31]
	v_mfma_f32_16x16x32_bf16 v[24:27], v[152:155], v[204:207], v[24:27]
	v_mfma_f32_16x16x32_bf16 v[20:23], v[174:177], v[204:207], v[20:23]
	v_mfma_f32_16x16x32_bf16 v[16:19], v[152:155], v[212:215], v[16:19]
	v_mfma_f32_16x16x32_bf16 v[12:15], v[174:177], v[212:215], v[12:15]
	v_mfma_f32_16x16x32_bf16 v[8:11], v[152:155], v[220:223], v[8:11]
	v_mfma_f32_16x16x32_bf16 v[4:7], v[174:177], v[220:223], v[4:7]
	v_mfma_f32_16x16x32_bf16 v[32:35], v[170:173], v[192:195], v[32:35]
	v_mfma_f32_16x16x32_bf16 v[28:31], v[178:181], v[192:195], v[28:31]
	v_mfma_f32_16x16x32_bf16 v[24:27], v[170:173], v[208:211], v[24:27]
	v_mfma_f32_16x16x32_bf16 v[20:23], v[178:181], v[208:211], v[20:23]
	v_mfma_f32_16x16x32_bf16 v[16:19], v[170:173], v[216:219], v[16:19]
	v_mfma_f32_16x16x32_bf16 v[12:15], v[178:181], v[216:219], v[12:15]
	v_mfma_f32_16x16x32_bf16 v[8:11], v[170:173], v[224:227], v[8:11]
	v_mfma_f32_16x16x32_bf16 v[4:7], v[178:181], v[224:227], v[4:7]

	s_barrier
	s_add_i32 s66, s66, 2
	s_add_u32 s10, s10, 0x100
	s_addc_u32 s11, s11, 0
	s_cmp_gt_u32 s66, 29
	s_cbranch_scc0 .LBB0_866
	s_and_b64 vcc, exec, s[12:13]
	s_cbranch_vccz .LBB0_869
	s_barrier
